# all flat_load/flat_store instructions (attention epilogues, LayerNorm phase loads) converted to global_ address-space forms
# speedup vs baseline: 1.0031x; 1.0031x over previous
.LBB0_669:
	s_or_b64 exec, exec, s[48:49]
	v_pk_mul_f32 v[78:79], v[130:131], v[72:73] op_sel_hi:[1,0]
	v_pk_mul_f32 v[80:81], v[132:133], v[72:73] op_sel_hi:[1,0]
	v_pk_fma_f32 v[78:79], v[2:3], v[78:79], v[10:11]
	v_pk_fma_f32 v[80:81], v[4:5], v[80:81], v[12:13]
	v_cvt_pk_bf16_f32 v78, v78, v79
	v_cvt_pk_bf16_f32 v79, v80, v81
	v_add_co_u32_e32 v80, vcc, 0xffffe1fc, v98
	s_movk_i32 s5, 0xe3fc
	s_nop 0
	v_addc_co_u32_e32 v81, vcc, -1, v99, vcc
	global_store_dwordx2 v[80:81], v[78:79], off
	v_pk_mul_f32 v[78:79], v[126:127], v[72:73] op_sel_hi:[1,0]
	v_pk_mul_f32 v[80:81], v[128:129], v[72:73] op_sel_hi:[1,0]
	v_pk_fma_f32 v[78:79], v[6:7], v[78:79], v[14:15]
	v_pk_fma_f32 v[80:81], v[8:9], v[80:81], v[16:17]
	v_cvt_pk_bf16_f32 v78, v78, v79
	v_cvt_pk_bf16_f32 v79, v80, v81
	v_add_co_u32_e32 v80, vcc, s5, v98
	s_movk_i32 s5, 0xe5fc
	s_nop 0
	v_addc_co_u32_e32 v81, vcc, -1, v99, vcc
	global_store_dwordx2 v[80:81], v[78:79], off
	v_pk_mul_f32 v[78:79], v[122:123], v[72:73] op_sel_hi:[1,0]
	v_pk_mul_f32 v[80:81], v[124:125], v[72:73] op_sel_hi:[1,0]
	v_pk_fma_f32 v[78:79], v[18:19], v[78:79], v[26:27]
	v_pk_fma_f32 v[80:81], v[20:21], v[80:81], v[28:29]
	v_cvt_pk_bf16_f32 v78, v78, v79
	v_cvt_pk_bf16_f32 v79, v80, v81
	v_add_co_u32_e32 v80, vcc, s5, v98
	s_movk_i32 s5, 0xe7fc
	s_nop 0
	v_addc_co_u32_e32 v81, vcc, -1, v99, vcc
	global_store_dwordx2 v[80:81], v[78:79], off
	v_pk_mul_f32 v[78:79], v[114:115], v[72:73] op_sel_hi:[1,0]
	v_pk_mul_f32 v[72:73], v[116:117], v[72:73] op_sel_hi:[1,0]
	v_pk_fma_f32 v[78:79], v[22:23], v[78:79], v[30:31]
	v_pk_fma_f32 v[72:73], v[24:25], v[72:73], v[32:33]
	v_cvt_pk_bf16_f32 v78, v78, v79
	v_cvt_pk_bf16_f32 v79, v72, v73
	v_add_co_u32_e32 v72, vcc, s5, v98
	s_movk_i32 s5, 0xe9fc
	s_nop 0
	v_addc_co_u32_e32 v73, vcc, -1, v99, vcc
	global_store_dwordx2 v[72:73], v[78:79], off
	v_pk_mul_f32 v[72:73], v[118:119], v[70:71] op_sel_hi:[1,0]
	v_pk_mul_f32 v[78:79], v[120:121], v[70:71] op_sel_hi:[1,0]
	v_pk_fma_f32 v[72:73], v[2:3], v[72:73], v[10:11]
	v_pk_fma_f32 v[78:79], v[4:5], v[78:79], v[12:13]
	v_cvt_pk_bf16_f32 v72, v72, v73
	v_cvt_pk_bf16_f32 v73, v78, v79
	v_add_co_u32_e32 v78, vcc, s5, v98
	s_movk_i32 s5, 0xebfc
	s_nop 0
	v_addc_co_u32_e32 v79, vcc, -1, v99, vcc
	global_store_dwordx2 v[78:79], v[72:73], off
	v_pk_mul_f32 v[72:73], v[110:111], v[70:71] op_sel_hi:[1,0]
	v_pk_mul_f32 v[78:79], v[112:113], v[70:71] op_sel_hi:[1,0]
	v_pk_fma_f32 v[72:73], v[6:7], v[72:73], v[14:15]
	v_pk_fma_f32 v[78:79], v[8:9], v[78:79], v[16:17]
	v_cvt_pk_bf16_f32 v72, v72, v73
	v_cvt_pk_bf16_f32 v73, v78, v79
	v_add_co_u32_e32 v78, vcc, s5, v98
	s_movk_i32 s5, 0xedfc
	s_nop 0
	v_addc_co_u32_e32 v79, vcc, -1, v99, vcc
	global_store_dwordx2 v[78:79], v[72:73], off
	v_pk_mul_f32 v[72:73], v[106:107], v[70:71] op_sel_hi:[1,0]
	v_pk_mul_f32 v[78:79], v[108:109], v[70:71] op_sel_hi:[1,0]
	v_pk_fma_f32 v[72:73], v[18:19], v[72:73], v[26:27]
	v_pk_fma_f32 v[78:79], v[20:21], v[78:79], v[28:29]
	v_cvt_pk_bf16_f32 v72, v72, v73
	v_cvt_pk_bf16_f32 v73, v78, v79
	v_add_co_u32_e32 v78, vcc, s5, v98
	v_pk_mul_f32 v[62:63], v[62:63], v[70:71] op_sel_hi:[1,0]
	v_pk_mul_f32 v[64:65], v[64:65], v[70:71] op_sel_hi:[1,0]
	v_addc_co_u32_e32 v79, vcc, -1, v99, vcc
	v_pk_fma_f32 v[62:63], v[22:23], v[62:63], v[30:31]
	v_pk_fma_f32 v[64:65], v[24:25], v[64:65], v[32:33]
	s_movk_i32 s5, 0xeffc
	v_cvt_pk_bf16_f32 v62, v62, v63
	v_cvt_pk_bf16_f32 v63, v64, v65
	v_add_co_u32_e32 v64, vcc, s5, v98
	s_movk_i32 s5, 0xf1fc
	s_nop 0
	v_addc_co_u32_e32 v65, vcc, -1, v99, vcc
	global_store_dwordx2 v[64:65], v[62:63], off
	v_pk_mul_f32 v[62:63], v[66:67], v[76:77] op_sel_hi:[1,0]
	v_pk_mul_f32 v[64:65], v[68:69], v[76:77] op_sel_hi:[1,0]
	v_pk_fma_f32 v[62:63], v[2:3], v[62:63], v[10:11]
	v_pk_fma_f32 v[64:65], v[4:5], v[64:65], v[12:13]
	v_cvt_pk_bf16_f32 v62, v62, v63
	v_cvt_pk_bf16_f32 v63, v64, v65
	v_add_co_u32_e32 v64, vcc, s5, v98
	v_pk_mul_f32 v[58:59], v[58:59], v[76:77] op_sel_hi:[1,0]
	v_pk_mul_f32 v[60:61], v[60:61], v[76:77] op_sel_hi:[1,0]
	v_addc_co_u32_e32 v65, vcc, -1, v99, vcc
	v_pk_fma_f32 v[58:59], v[6:7], v[58:59], v[14:15]
	v_pk_fma_f32 v[60:61], v[8:9], v[60:61], v[16:17]
	s_movk_i32 s5, 0xf3fc
	v_cvt_pk_bf16_f32 v58, v58, v59
	v_cvt_pk_bf16_f32 v59, v60, v61
	v_add_co_u32_e32 v60, vcc, s5, v98
	v_pk_mul_f32 v[54:55], v[54:55], v[76:77] op_sel_hi:[1,0]
	v_pk_mul_f32 v[56:57], v[56:57], v[76:77] op_sel_hi:[1,0]
	v_addc_co_u32_e32 v61, vcc, -1, v99, vcc
	v_pk_fma_f32 v[54:55], v[18:19], v[54:55], v[26:27]
	v_pk_fma_f32 v[56:57], v[20:21], v[56:57], v[28:29]
	s_movk_i32 s5, 0xf5fc
	v_cvt_pk_bf16_f32 v54, v54, v55
	v_cvt_pk_bf16_f32 v55, v56, v57
	v_add_co_u32_e32 v56, vcc, s5, v98
	v_pk_mul_f32 v[46:47], v[46:47], v[76:77] op_sel_hi:[1,0]
	v_pk_mul_f32 v[48:49], v[48:49], v[76:77] op_sel_hi:[1,0]
	v_addc_co_u32_e32 v57, vcc, -1, v99, vcc
	v_pk_fma_f32 v[46:47], v[22:23], v[46:47], v[30:31]
	v_pk_fma_f32 v[48:49], v[24:25], v[48:49], v[32:33]
	s_movk_i32 s5, 0xf7fc
	v_cvt_pk_bf16_f32 v46, v46, v47
	v_cvt_pk_bf16_f32 v47, v48, v49
	v_add_co_u32_e32 v48, vcc, s5, v98
	s_movk_i32 s5, 0xf9fc
	s_nop 0
	v_addc_co_u32_e32 v49, vcc, -1, v99, vcc
	global_store_dwordx2 v[48:49], v[46:47], off
	v_pk_mul_f32 v[46:47], v[50:51], v[74:75] op_sel_hi:[1,0]
	v_pk_mul_f32 v[48:49], v[52:53], v[74:75] op_sel_hi:[1,0]
	v_pk_fma_f32 v[46:47], v[2:3], v[46:47], v[10:11]
	v_pk_fma_f32 v[48:49], v[4:5], v[48:49], v[12:13]
	v_cvt_pk_bf16_f32 v46, v46, v47
	v_cvt_pk_bf16_f32 v47, v48, v49
	v_add_co_u32_e32 v48, vcc, s5, v98
	v_pk_mul_f32 v[42:43], v[42:43], v[74:75] op_sel_hi:[1,0]
	v_pk_mul_f32 v[44:45], v[44:45], v[74:75] op_sel_hi:[1,0]
	v_addc_co_u32_e32 v49, vcc, -1, v99, vcc
	v_pk_fma_f32 v[42:43], v[6:7], v[42:43], v[14:15]
	v_pk_fma_f32 v[44:45], v[8:9], v[44:45], v[16:17]
	s_movk_i32 s5, 0xfbfc
	v_cvt_pk_bf16_f32 v42, v42, v43
	v_cvt_pk_bf16_f32 v43, v44, v45
	v_add_co_u32_e32 v44, vcc, s5, v98
	v_pk_mul_f32 v[38:39], v[38:39], v[74:75] op_sel_hi:[1,0]
	v_pk_mul_f32 v[40:41], v[40:41], v[74:75] op_sel_hi:[1,0]
	v_addc_co_u32_e32 v45, vcc, -1, v99, vcc
	v_pk_fma_f32 v[38:39], v[18:19], v[38:39], v[26:27]
	v_pk_fma_f32 v[40:41], v[20:21], v[40:41], v[28:29]
	s_movk_i32 s5, 0xfdfc
	v_cvt_pk_bf16_f32 v38, v38, v39
	v_cvt_pk_bf16_f32 v39, v40, v41
	v_add_co_u32_e32 v40, vcc, s5, v98
	v_pk_mul_f32 v[34:35], v[34:35], v[74:75] op_sel_hi:[1,0]
	v_pk_mul_f32 v[36:37], v[36:37], v[74:75] op_sel_hi:[1,0]
	v_addc_co_u32_e32 v41, vcc, -1, v99, vcc
	v_pk_fma_f32 v[34:35], v[22:23], v[34:35], v[30:31]
	v_pk_fma_f32 v[36:37], v[24:25], v[36:37], v[32:33]
	v_cvt_pk_bf16_f32 v34, v34, v35
	v_cvt_pk_bf16_f32 v35, v36, v37
	v_add_co_u32_e32 v36, vcc, -4, v98
	s_add_i32 s4, s4, s14
	s_nop 0
	v_addc_co_u32_e32 v37, vcc, -1, v99, vcc
	v_lshl_add_u64 v[98:99], v[98:99], 0, s[16:17]
	s_cmpk_gt_i32 s4, 0x7fff
	v_lshl_add_u64 v[100:101], v[100:101], 0, s[62:63]
	global_store_dwordx2 v[78:79], v[72:73], off
	global_store_dwordx2 v[64:65], v[62:63], off
	global_store_dwordx2 v[60:61], v[58:59], off
	global_store_dwordx2 v[56:57], v[54:55], off
	global_store_dwordx2 v[48:49], v[46:47], off
	global_store_dwordx2 v[44:45], v[42:43], off
	global_store_dwordx2 v[40:41], v[38:39], off
	global_store_dwordx2 v[36:37], v[34:35], off
	s_cbranch_scc1 .LBB0_673
.LBB0_670:
	v_add_co_u32_e32 v34, vcc, 0xffffc3f8, v100
	s_movk_i32 s5, 0xc7f8
	s_nop 0
	v_addc_co_u32_e32 v35, vcc, -1, v101, vcc
	v_add_co_u32_e32 v38, vcc, s5, v100
	global_load_dwordx4 v[34:37], v[34:35], off
	s_nop 0
	v_addc_co_u32_e32 v39, vcc, -1, v101, vcc
	global_load_dwordx4 v[38:41], v[38:39], off
	s_movk_i32 s5, 0xcbf8
	s_mov_b32 s10, 0x3727c5ac
	s_waitcnt vmcnt(0) lgkmcnt(0)
	v_add_f32_e32 v0, v34, v35
	v_add_f32_e32 v0, v0, v36
	v_add_f32_e32 v0, v0, v37
	v_add_f32_e32 v42, v38, v39
	v_add_f32_e32 v42, v42, v40
	v_add_f32_e32 v0, 0, v0
	v_add_f32_e32 v42, v42, v41
	v_add_f32_e32 v0, v0, v42
	v_add_co_u32_e32 v42, vcc, s5, v100
	s_movk_i32 s5, 0xcff8
	s_nop 0
	v_addc_co_u32_e32 v43, vcc, -1, v101, vcc
	global_load_dwordx4 v[42:45], v[42:43], off
	s_waitcnt vmcnt(0) lgkmcnt(0)
	v_add_f32_e32 v46, v42, v43
	v_add_f32_e32 v46, v46, v44
	v_add_f32_e32 v46, v46, v45
	v_add_f32_e32 v0, v0, v46
	v_add_co_u32_e32 v46, vcc, s5, v100
	s_movk_i32 s5, 0xd7f8
	s_nop 0
	v_addc_co_u32_e32 v47, vcc, -1, v101, vcc
	global_load_dwordx4 v[46:49], v[46:47], off
	s_waitcnt vmcnt(0) lgkmcnt(0)
	v_add_f32_e32 v50, v46, v47
	v_add_f32_e32 v50, v50, v48
	v_add_f32_e32 v50, v50, v49
	v_add_f32_e32 v0, v0, v50
	ds_swizzle_b32 v50, v0 offset:swizzle(SWAP,1)
	s_waitcnt lgkmcnt(0)
	v_add_f32_e32 v0, v0, v50
	ds_swizzle_b32 v50, v0 offset:swizzle(SWAP,2)
	s_waitcnt lgkmcnt(0)
	v_add_f32_e32 v0, v0, v50
	ds_swizzle_b32 v50, v0 offset:swizzle(SWAP,4)
	s_waitcnt lgkmcnt(0)
	v_add_f32_e32 v0, v0, v50
	ds_swizzle_b32 v50, v0 offset:swizzle(SWAP,8)
	s_waitcnt lgkmcnt(0)
	v_add_f32_e32 v0, v0, v50
	ds_swizzle_b32 v50, v0 offset:swizzle(SWAP,16)
	s_waitcnt lgkmcnt(0)
	v_add_f32_e32 v0, v0, v50
	v_add_co_u32_e32 v50, vcc, s94, v100
	s_nop 1
	v_addc_co_u32_e32 v51, vcc, -1, v101, vcc
	global_load_dwordx4 v[50:53], v[50:51], off
	s_waitcnt vmcnt(0) lgkmcnt(0)
	v_add_f32_e32 v54, v50, v51
	v_add_f32_e32 v54, v54, v52
	v_add_f32_e32 v54, v54, v53
	v_add_f32_e32 v58, 0, v54
	v_add_co_u32_e32 v54, vcc, s5, v100
	s_movk_i32 s5, 0xdbf8
	s_nop 0
	v_addc_co_u32_e32 v55, vcc, -1, v101, vcc
	global_load_dwordx4 v[54:57], v[54:55], off
	s_waitcnt vmcnt(0) lgkmcnt(0)
	v_add_f32_e32 v59, v54, v55
	v_add_f32_e32 v59, v59, v56
	v_add_f32_e32 v59, v59, v57
	v_add_f32_e32 v62, v58, v59
	v_add_co_u32_e32 v58, vcc, s5, v100
	s_movk_i32 s5, 0xdff8
	s_nop 0
	v_addc_co_u32_e32 v59, vcc, -1, v101, vcc
	global_load_dwordx4 v[58:61], v[58:59], off
	s_waitcnt vmcnt(0) lgkmcnt(0)
	v_add_f32_e32 v63, v58, v59
	v_add_f32_e32 v63, v63, v60
	v_add_f32_e32 v63, v63, v61
	v_add_f32_e32 v66, v62, v63
	v_add_co_u32_e32 v62, vcc, s5, v100
	s_movk_i32 s5, 0xe7f8
	s_nop 0
	v_addc_co_u32_e32 v63, vcc, -1, v101, vcc
	global_load_dwordx4 v[62:65], v[62:63], off
	s_waitcnt vmcnt(0) lgkmcnt(0)
	v_add_f32_e32 v67, v62, v63
	v_add_f32_e32 v67, v67, v64
	v_add_f32_e32 v67, v67, v65
	v_add_f32_e32 v102, v66, v67
	v_add_co_u32_e32 v66, vcc, s89, v100
	s_nop 1
	v_addc_co_u32_e32 v67, vcc, -1, v101, vcc
	global_load_dwordx4 v[66:69], v[66:67], off
	s_waitcnt vmcnt(0) lgkmcnt(0)
	v_add_f32_e32 v70, v66, v67
	v_add_f32_e32 v70, v70, v68
	v_add_f32_e32 v70, v70, v69
	v_add_f32_e32 v74, 0, v70
	v_add_co_u32_e32 v70, vcc, s5, v100
	s_movk_i32 s5, 0xebf8
	s_nop 0
	v_addc_co_u32_e32 v71, vcc, -1, v101, vcc
	global_load_dwordx4 v[70:73], v[70:71], off
	s_waitcnt vmcnt(0) lgkmcnt(0)
	v_add_f32_e32 v75, v70, v71
	v_add_f32_e32 v75, v75, v72
	v_add_f32_e32 v75, v75, v73
	v_add_f32_e32 v78, v74, v75
	v_add_co_u32_e32 v74, vcc, s5, v100
	s_movk_i32 s5, 0xeff8
	s_nop 0
	v_addc_co_u32_e32 v75, vcc, -1, v101, vcc
	global_load_dwordx4 v[74:77], v[74:75], off
	s_waitcnt vmcnt(0) lgkmcnt(0)
	v_add_f32_e32 v79, v74, v75
	v_add_f32_e32 v79, v79, v76
	v_add_f32_e32 v79, v79, v77
	v_add_f32_e32 v82, v78, v79
	v_add_co_u32_e32 v78, vcc, s5, v100
	s_movk_i32 s5, 0xf7f8
	s_nop 0
	v_addc_co_u32_e32 v79, vcc, -1, v101, vcc
	global_load_dwordx4 v[78:81], v[78:79], off
	s_waitcnt vmcnt(0) lgkmcnt(0)
	v_add_f32_e32 v83, v78, v79
	v_add_f32_e32 v83, v83, v80
	v_add_f32_e32 v83, v83, v81
	v_add_f32_e32 v104, v82, v83
	v_add_co_u32_e32 v82, vcc, s90, v100
	s_nop 1
	v_addc_co_u32_e32 v83, vcc, -1, v101, vcc
	global_load_dwordx4 v[82:85], v[82:83], off
	s_waitcnt vmcnt(0) lgkmcnt(0)
	v_add_f32_e32 v86, v82, v83
	v_add_f32_e32 v86, v86, v84
	v_add_f32_e32 v86, v86, v85
	v_add_f32_e32 v90, 0, v86
	v_add_co_u32_e32 v86, vcc, s5, v100
	s_movk_i32 s5, 0xfbf8
	s_nop 0
	v_addc_co_u32_e32 v87, vcc, -1, v101, vcc
	global_load_dwordx4 v[86:89], v[86:87], off
	s_waitcnt vmcnt(0) lgkmcnt(0)
	v_add_f32_e32 v91, v86, v87
	v_add_f32_e32 v91, v91, v88
	v_add_f32_e32 v91, v91, v89
	v_add_f32_e32 v94, v90, v91
	v_add_co_u32_e32 v90, vcc, s5, v100
	s_mov_b32 s5, 0x800000
	s_nop 0
	v_addc_co_u32_e32 v91, vcc, -1, v101, vcc
	global_load_dwordx4 v[90:93], v[90:91], off
	s_waitcnt vmcnt(0) lgkmcnt(0)
	v_add_f32_e32 v95, v90, v91
	v_add_f32_e32 v95, v95, v92
	v_add_f32_e32 v95, v95, v93
	v_add_f32_e32 v105, v94, v95
	v_add_co_u32_e32 v94, vcc, -8, v100
	s_nop 1
	v_addc_co_u32_e32 v95, vcc, -1, v101, vcc
	global_load_dwordx4 v[94:97], v[94:95], off
	s_waitcnt vmcnt(0) lgkmcnt(0)
	v_add_f32_e32 v106, v94, v95
	v_add_f32_e32 v106, v106, v96
	v_add_f32_e32 v106, v106, v97
	v_add_f32_e32 v105, v105, v106
	v_mov_b32_e32 v106, v0
	s_nop 1
	v_permlane32_swap_b32_e32 v0, v106
	v_add_f32_e32 v0, v0, v106
	ds_swizzle_b32 v106, v102 offset:swizzle(SWAP,1)
	v_mul_f32_e32 v0, 0x3a800000, v0
	v_pk_add_f32 v[130:131], v[34:35], v[0:1] op_sel_hi:[1,0] neg_lo:[0,1] neg_hi:[0,1]
	v_pk_add_f32 v[126:127], v[38:39], v[0:1] op_sel_hi:[1,0] neg_lo:[0,1] neg_hi:[0,1]
	v_pk_add_f32 v[132:133], v[36:37], v[0:1] op_sel_hi:[1,0] neg_lo:[0,1] neg_hi:[0,1]
	s_waitcnt lgkmcnt(0)
	v_add_f32_e32 v102, v102, v106
	ds_swizzle_b32 v106, v102 offset:swizzle(SWAP,2)
	v_mov_b32_e32 v36, v131
	v_mov_b32_e32 v37, v127
	v_pk_add_f32 v[128:129], v[40:41], v[0:1] op_sel_hi:[1,0] neg_lo:[0,1] neg_hi:[0,1]
	v_mov_b32_e32 v34, v130
	s_waitcnt lgkmcnt(0)
	v_add_f32_e32 v102, v102, v106
	ds_swizzle_b32 v106, v102 offset:swizzle(SWAP,4)
	v_mov_b32_e32 v35, v126
	v_pk_mul_f32 v[36:37], v[36:37], v[36:37]
	v_pk_add_f32 v[122:123], v[42:43], v[0:1] op_sel_hi:[1,0] neg_lo:[0,1] neg_hi:[0,1]
	v_pk_fma_f32 v[34:35], v[34:35], v[34:35], v[36:37]
	s_waitcnt lgkmcnt(0)
	v_add_f32_e32 v102, v102, v106
	ds_swizzle_b32 v106, v102 offset:swizzle(SWAP,8)
	v_mov_b32_e32 v36, v132
	v_mov_b32_e32 v37, v128
	v_pk_add_f32 v[114:115], v[46:47], v[0:1] op_sel_hi:[1,0] neg_lo:[0,1] neg_hi:[0,1]
	v_pk_fma_f32 v[34:35], v[36:37], v[36:37], v[34:35]
	s_waitcnt lgkmcnt(0)
	v_add_f32_e32 v102, v102, v106
	ds_swizzle_b32 v106, v102 offset:swizzle(SWAP,16)
	v_mov_b32_e32 v36, v133
	v_mov_b32_e32 v37, v129
	v_mov_b32_e32 v38, v115
	v_mov_b32_e32 v39, v123
	s_waitcnt lgkmcnt(0)
	v_add_f32_e32 v102, v102, v106
	v_mov_b32_e32 v106, v102
	v_pk_fma_f32 v[34:35], v[36:37], v[36:37], v[34:35]
	s_nop 0
	v_permlane32_swap_b32_e32 v102, v106
	v_add_f32_e32 v102, v102, v106
	ds_swizzle_b32 v106, v104 offset:swizzle(SWAP,1)
	v_pk_add_f32 v[124:125], v[44:45], v[0:1] op_sel_hi:[1,0] neg_lo:[0,1] neg_hi:[0,1]
	v_pk_add_f32 v[116:117], v[48:49], v[0:1] op_sel_hi:[1,0] neg_lo:[0,1] neg_hi:[0,1]
	v_mov_b32_e32 v36, v114
	v_mov_b32_e32 v37, v122
	s_waitcnt lgkmcnt(0)
	v_add_f32_e32 v104, v104, v106
	ds_swizzle_b32 v106, v104 offset:swizzle(SWAP,2)
	v_pk_mul_f32 v[38:39], v[38:39], v[38:39]
	v_mul_f32_e32 v102, 0x3a800000, v102
	v_pk_fma_f32 v[36:37], v[36:37], v[36:37], v[38:39]
	v_mov_b32_e32 v38, v116
	s_waitcnt lgkmcnt(0)
	v_add_f32_e32 v104, v104, v106
	ds_swizzle_b32 v106, v104 offset:swizzle(SWAP,4)
	v_mov_b32_e32 v39, v124
	v_pk_fma_f32 v[36:37], v[38:39], v[38:39], v[36:37]
	v_mov_b32_e32 v38, v117
	v_mov_b32_e32 v39, v125
	s_waitcnt lgkmcnt(0)
	v_add_f32_e32 v104, v104, v106
	ds_swizzle_b32 v106, v104 offset:swizzle(SWAP,8)
	v_pk_fma_f32 v[36:37], v[38:39], v[38:39], v[36:37]
	v_add_f32_e32 v34, v34, v35
	v_add_f32_e32 v34, v37, v34
	v_pk_add_f32 v[118:119], v[50:51], v[102:103] op_sel_hi:[1,0] neg_lo:[0,1] neg_hi:[0,1]
	s_waitcnt lgkmcnt(0)
	v_add_f32_e32 v104, v104, v106
	ds_swizzle_b32 v106, v104 offset:swizzle(SWAP,16)
	v_pk_add_f32 v[110:111], v[54:55], v[102:103] op_sel_hi:[1,0] neg_lo:[0,1] neg_hi:[0,1]
	v_pk_add_f32 v[120:121], v[52:53], v[102:103] op_sel_hi:[1,0] neg_lo:[0,1] neg_hi:[0,1]
	v_mov_b32_e32 v37, v111
	v_pk_add_f32 v[112:113], v[56:57], v[102:103] op_sel_hi:[1,0] neg_lo:[0,1] neg_hi:[0,1]
	s_waitcnt lgkmcnt(0)
	v_add_f32_e32 v104, v104, v106
	v_mov_b32_e32 v106, v104
	v_mov_b32_e32 v35, v110
	s_nop 0
	v_permlane32_swap_b32_e32 v104, v106
	v_add_f32_e32 v104, v104, v106
	ds_swizzle_b32 v106, v105 offset:swizzle(SWAP,1)
	v_pk_add_f32 v[62:63], v[62:63], v[102:103] op_sel_hi:[1,0] neg_lo:[0,1] neg_hi:[0,1]
	v_pk_add_f32 v[108:109], v[60:61], v[102:103] op_sel_hi:[1,0] neg_lo:[0,1] neg_hi:[0,1]
	v_mov_b32_e32 v38, v63
	v_pk_add_f32 v[64:65], v[64:65], v[102:103] op_sel_hi:[1,0] neg_lo:[0,1] neg_hi:[0,1]
	s_waitcnt lgkmcnt(0)
	v_add_f32_e32 v105, v105, v106
	ds_swizzle_b32 v106, v105 offset:swizzle(SWAP,2)
	v_mul_f32_e32 v104, 0x3a800000, v104
	s_waitcnt lgkmcnt(0)
	v_add_f32_e32 v105, v105, v106
	ds_swizzle_b32 v106, v105 offset:swizzle(SWAP,4)
	s_waitcnt lgkmcnt(0)
	v_add_f32_e32 v105, v105, v106
	ds_swizzle_b32 v106, v105 offset:swizzle(SWAP,8)
	s_waitcnt lgkmcnt(0)
	v_add_f32_e32 v105, v105, v106
	ds_swizzle_b32 v106, v105 offset:swizzle(SWAP,16)
	s_waitcnt lgkmcnt(0)
	v_add_f32_e32 v105, v105, v106
	v_mov_b32_e32 v106, v105
	s_nop 1
	v_permlane32_swap_b32_e32 v105, v106
	v_add_f32_e32 v105, v105, v106
	v_mul_f32_e32 v134, 0x3a800000, v105
	v_add_f32_e32 v105, v36, v34
	v_mov_b32_e32 v36, v119
	v_mov_b32_e32 v34, v118
	v_pk_mul_f32 v[36:37], v[36:37], v[36:37]
	v_pk_add_f32 v[106:107], v[58:59], v[102:103] op_sel_hi:[1,0] neg_lo:[0,1] neg_hi:[0,1]
	v_pk_fma_f32 v[34:35], v[34:35], v[34:35], v[36:37]
	v_mov_b32_e32 v36, v120
	v_mov_b32_e32 v37, v112
	v_pk_fma_f32 v[34:35], v[36:37], v[36:37], v[34:35]
	v_mov_b32_e32 v36, v121
	v_mov_b32_e32 v37, v113
	v_mov_b32_e32 v39, v107
	v_pk_fma_f32 v[34:35], v[36:37], v[36:37], v[34:35]
	v_mov_b32_e32 v36, v62
	v_mov_b32_e32 v37, v106
	v_pk_mul_f32 v[38:39], v[38:39], v[38:39]
	v_add_f32_e32 v34, v34, v35
	v_pk_fma_f32 v[36:37], v[36:37], v[36:37], v[38:39]
	v_mov_b32_e32 v38, v64
	v_mov_b32_e32 v39, v108
	v_pk_fma_f32 v[36:37], v[38:39], v[38:39], v[36:37]
	v_mov_b32_e32 v38, v65
	v_mov_b32_e32 v39, v109
	v_pk_fma_f32 v[36:37], v[38:39], v[38:39], v[36:37]
	v_pk_add_f32 v[66:67], v[66:67], v[104:105] op_sel_hi:[1,0] neg_lo:[0,1] neg_hi:[0,1]
	v_add_f32_e32 v34, v37, v34
	v_pk_add_f32 v[58:59], v[70:71], v[104:105] op_sel_hi:[1,0] neg_lo:[0,1] neg_hi:[0,1]
	v_add_f32_e32 v135, v36, v34
	v_mov_b32_e32 v36, v67
	v_mov_b32_e32 v37, v59
	v_pk_add_f32 v[68:69], v[68:69], v[104:105] op_sel_hi:[1,0] neg_lo:[0,1] neg_hi:[0,1]
	v_pk_add_f32 v[60:61], v[72:73], v[104:105] op_sel_hi:[1,0] neg_lo:[0,1] neg_hi:[0,1]
	v_mov_b32_e32 v34, v66
	v_mov_b32_e32 v35, v58
	v_pk_mul_f32 v[36:37], v[36:37], v[36:37]
	v_pk_add_f32 v[54:55], v[74:75], v[104:105] op_sel_hi:[1,0] neg_lo:[0,1] neg_hi:[0,1]
	v_pk_fma_f32 v[34:35], v[34:35], v[34:35], v[36:37]
	v_mov_b32_e32 v36, v68
	v_mov_b32_e32 v37, v60
	v_pk_add_f32 v[46:47], v[78:79], v[104:105] op_sel_hi:[1,0] neg_lo:[0,1] neg_hi:[0,1]
	v_pk_fma_f32 v[34:35], v[36:37], v[36:37], v[34:35]
	v_mov_b32_e32 v36, v69
	v_mov_b32_e32 v37, v61
	v_mov_b32_e32 v38, v47
	v_mov_b32_e32 v39, v55
	v_pk_fma_f32 v[34:35], v[36:37], v[36:37], v[34:35]
	v_pk_add_f32 v[56:57], v[76:77], v[104:105] op_sel_hi:[1,0] neg_lo:[0,1] neg_hi:[0,1]
	v_pk_add_f32 v[48:49], v[80:81], v[104:105] op_sel_hi:[1,0] neg_lo:[0,1] neg_hi:[0,1]
	v_mov_b32_e32 v36, v46
	v_mov_b32_e32 v37, v54
	v_pk_mul_f32 v[38:39], v[38:39], v[38:39]
	v_add_f32_e32 v34, v34, v35
	v_pk_fma_f32 v[36:37], v[36:37], v[36:37], v[38:39]
	v_mov_b32_e32 v38, v48
	v_mov_b32_e32 v39, v56
	v_pk_fma_f32 v[36:37], v[38:39], v[38:39], v[36:37]
	v_mov_b32_e32 v38, v49
	v_mov_b32_e32 v39, v57
	v_pk_fma_f32 v[36:37], v[38:39], v[38:39], v[36:37]
	v_pk_add_f32 v[50:51], v[82:83], v[134:135] op_sel_hi:[1,0] neg_lo:[0,1] neg_hi:[0,1]
	v_add_f32_e32 v34, v37, v34
	v_pk_add_f32 v[42:43], v[86:87], v[134:135] op_sel_hi:[1,0] neg_lo:[0,1] neg_hi:[0,1]
	v_add_f32_e32 v76, v36, v34
	v_mov_b32_e32 v36, v51
	v_mov_b32_e32 v37, v43
	v_pk_add_f32 v[52:53], v[84:85], v[134:135] op_sel_hi:[1,0] neg_lo:[0,1] neg_hi:[0,1]
	v_pk_add_f32 v[44:45], v[88:89], v[134:135] op_sel_hi:[1,0] neg_lo:[0,1] neg_hi:[0,1]
	v_mov_b32_e32 v34, v50
	v_mov_b32_e32 v35, v42
	v_pk_mul_f32 v[36:37], v[36:37], v[36:37]
	v_pk_add_f32 v[38:39], v[90:91], v[134:135] op_sel_hi:[1,0] neg_lo:[0,1] neg_hi:[0,1]
	v_pk_fma_f32 v[34:35], v[34:35], v[34:35], v[36:37]
	v_mov_b32_e32 v36, v52
	v_mov_b32_e32 v37, v44
	v_pk_fma_f32 v[34:35], v[36:37], v[36:37], v[34:35]
	v_mov_b32_e32 v36, v53
	v_mov_b32_e32 v37, v45
	v_pk_fma_f32 v[70:71], v[36:37], v[36:37], v[34:35]
	v_pk_add_f32 v[34:35], v[94:95], v[134:135] op_sel_hi:[1,0] neg_lo:[0,1] neg_hi:[0,1]
	v_mov_b32_e32 v75, v39
	v_mov_b32_e32 v74, v35
	v_pk_add_f32 v[40:41], v[92:93], v[134:135] op_sel_hi:[1,0] neg_lo:[0,1] neg_hi:[0,1]
	v_pk_add_f32 v[36:37], v[96:97], v[134:135] op_sel_hi:[1,0] neg_lo:[0,1] neg_hi:[0,1]
	v_mov_b32_e32 v72, v34
	v_mov_b32_e32 v73, v38
	v_pk_mul_f32 v[74:75], v[74:75], v[74:75]
	v_add_f32_e32 v70, v70, v71
	v_pk_fma_f32 v[72:73], v[72:73], v[72:73], v[74:75]
	v_mov_b32_e32 v74, v36
	v_mov_b32_e32 v75, v40
	v_pk_fma_f32 v[72:73], v[74:75], v[74:75], v[72:73]
	v_mov_b32_e32 v74, v37
	v_mov_b32_e32 v75, v41
	v_pk_fma_f32 v[72:73], v[74:75], v[74:75], v[72:73]
	v_mov_b64_e32 v[74:75], s[10:11]
	v_add_f32_e32 v70, v73, v70
	v_add_f32_e32 v78, v72, v70
	ds_swizzle_b32 v70, v105 offset:swizzle(SWAP,1)
	s_mov_b32 s10, 0x3a800000
	s_waitcnt lgkmcnt(0)
	v_add_f32_e32 v70, v105, v70
	ds_swizzle_b32 v71, v70 offset:swizzle(SWAP,2)
	s_waitcnt lgkmcnt(0)
	v_add_f32_e32 v70, v70, v71
	ds_swizzle_b32 v71, v70 offset:swizzle(SWAP,4)
	s_waitcnt lgkmcnt(0)
	v_add_f32_e32 v70, v70, v71
	ds_swizzle_b32 v71, v70 offset:swizzle(SWAP,8)
	s_waitcnt lgkmcnt(0)
	v_add_f32_e32 v70, v70, v71
	ds_swizzle_b32 v71, v70 offset:swizzle(SWAP,16)
	s_waitcnt lgkmcnt(0)
	v_add_f32_e32 v71, v70, v71
	ds_swizzle_b32 v70, v135 offset:swizzle(SWAP,1)
	v_mov_b32_e32 v73, v71
	s_waitcnt lgkmcnt(0)
	v_add_f32_e32 v70, v135, v70
	ds_swizzle_b32 v72, v70 offset:swizzle(SWAP,2)
	v_permlane32_swap_b32_e32 v71, v73
	s_waitcnt lgkmcnt(0)
	v_add_f32_e32 v70, v70, v72
	ds_swizzle_b32 v72, v70 offset:swizzle(SWAP,4)
	s_waitcnt lgkmcnt(0)
	v_add_f32_e32 v70, v70, v72
	ds_swizzle_b32 v72, v70 offset:swizzle(SWAP,8)
	s_waitcnt lgkmcnt(0)
	v_add_f32_e32 v70, v70, v72
	ds_swizzle_b32 v72, v70 offset:swizzle(SWAP,16)
	s_waitcnt lgkmcnt(0)
	v_add_f32_e32 v70, v70, v72
	v_mov_b32_e32 v72, v70
	s_nop 1
	v_permlane32_swap_b32_e32 v70, v72
	v_pk_add_f32 v[70:71], v[70:71], v[72:73]
	s_nop 0
	v_pk_fma_f32 v[70:71], v[70:71], s[10:11], v[74:75] op_sel_hi:[1,0,0]
	s_nop 0
	v_mul_f32_e32 v72, 0x4b800000, v71
	v_cmp_gt_f32_e64 s[48:49], s5, v71
	v_cmp_gt_f32_e32 vcc, s5, v70
	s_nop 0
	v_cndmask_b32_e64 v71, v71, v72, s[48:49]
	v_rsq_f32_e32 v71, v71
	s_nop 0
	v_mul_f32_e32 v72, 0x45800000, v71
	v_cndmask_b32_e64 v72, v71, v72, s[48:49]
	v_mul_f32_e32 v71, 0x4b800000, v70
	v_cndmask_b32_e32 v70, v70, v71, vcc
	v_rsq_f32_e32 v70, v70
	s_nop 0
	v_mul_f32_e32 v71, 0x45800000, v70
	v_cndmask_b32_e32 v70, v70, v71, vcc
	ds_swizzle_b32 v71, v76 offset:swizzle(SWAP,1)
	s_waitcnt lgkmcnt(0)
	v_add_f32_e32 v71, v76, v71
	ds_swizzle_b32 v73, v71 offset:swizzle(SWAP,2)
	s_waitcnt lgkmcnt(0)
	v_add_f32_e32 v71, v71, v73
	ds_swizzle_b32 v73, v71 offset:swizzle(SWAP,4)
	s_waitcnt lgkmcnt(0)
	v_add_f32_e32 v71, v71, v73
	ds_swizzle_b32 v73, v71 offset:swizzle(SWAP,8)
	s_waitcnt lgkmcnt(0)
	v_add_f32_e32 v71, v71, v73
	ds_swizzle_b32 v73, v71 offset:swizzle(SWAP,16)
	s_waitcnt lgkmcnt(0)
	v_add_f32_e32 v77, v71, v73
	ds_swizzle_b32 v71, v78 offset:swizzle(SWAP,1)
	v_mov_b32_e32 v79, v77
	s_waitcnt lgkmcnt(0)
	v_add_f32_e32 v71, v78, v71
	ds_swizzle_b32 v73, v71 offset:swizzle(SWAP,2)
	v_permlane32_swap_b32_e32 v77, v79
	s_waitcnt lgkmcnt(0)
	v_add_f32_e32 v71, v71, v73
	ds_swizzle_b32 v73, v71 offset:swizzle(SWAP,4)
	s_waitcnt lgkmcnt(0)
	v_add_f32_e32 v71, v71, v73
	ds_swizzle_b32 v73, v71 offset:swizzle(SWAP,8)
	s_waitcnt lgkmcnt(0)
	v_add_f32_e32 v71, v71, v73
	ds_swizzle_b32 v73, v71 offset:swizzle(SWAP,16)
	s_waitcnt lgkmcnt(0)
	v_add_f32_e32 v76, v71, v73
	v_mov_b32_e32 v78, v76
	s_nop 1
	v_permlane32_swap_b32_e32 v76, v78
	v_pk_add_f32 v[76:77], v[76:77], v[78:79]
	s_nop 0
	v_pk_fma_f32 v[74:75], v[76:77], s[10:11], v[74:75] op_sel_hi:[1,0,0]
	s_nop 0
	v_mul_f32_e32 v71, 0x4b800000, v75
	v_cmp_gt_f32_e64 s[48:49], s5, v75
	v_cmp_gt_f32_e32 vcc, s5, v74
	s_nop 0
	v_cndmask_b32_e64 v71, v75, v71, s[48:49]
	v_rsq_f32_e32 v71, v71
	s_nop 0
	v_mul_f32_e32 v73, 0x45800000, v71
	v_cndmask_b32_e64 v76, v71, v73, s[48:49]
	v_mul_f32_e32 v71, 0x4b800000, v74
	v_cndmask_b32_e32 v71, v74, v71, vcc
	v_rsq_f32_e32 v71, v71
	s_nop 0
	v_mul_f32_e32 v73, 0x45800000, v71
	v_cndmask_b32_e32 v74, v71, v73, vcc
	s_and_saveexec_b64 s[48:49], s[40:41]
	s_cbranch_execz .LBB0_669
	v_cndmask_b32_e64 v71, v134, v104, s[46:47]
	v_cndmask_b32_e64 v71, v71, v102, s[44:45]
	v_cndmask_b32_e64 v78, v71, v0, s[42:43]
	v_cndmask_b32_e64 v0, v74, v76, s[46:47]
	v_add_u32_e32 v80, s4, v103
	v_cndmask_b32_e64 v0, v0, v70, s[44:45]
	v_ashrrev_i32_e32 v81, 31, v80
	v_cndmask_b32_e64 v79, v0, v72, s[42:43]
	v_lshl_add_u64 v[80:81], v[80:81], 3, s[8:9]
	global_store_dwordx2 v[80:81], v[78:79], off
	s_branch .LBB0_669

.LBB0_724:
	s_nop 0
	v_cvt_pk_bf16_f32 v34, v34, v35
	v_cvt_pk_bf16_f32 v35, v36, v37
	v_add_co_u32_e32 v36, vcc, -4, v98
	s_add_i32 s4, s4, s16
	s_nop 0
	v_addc_co_u32_e32 v37, vcc, -1, v99, vcc
	v_lshl_add_u64 v[98:99], v[98:99], 0, s[52:53]
	s_cmpk_gt_i32 s4, 0x7fff
	v_lshl_add_u64 v[100:101], v[100:101], 0, s[54:55]
	global_store_dwordx2 v[36:37], v[34:35], off
	s_cbranch_scc1 .LBB0_759
.LBB0_725:
	v_add_co_u32_e32 v46, vcc, s90, v100
	s_movk_i32 s5, 0xc3f8
	s_nop 0
	v_addc_co_u32_e32 v47, vcc, -1, v101, vcc
	global_load_dwordx4 v[38:41], v[46:47], off offset:2048
	v_add_co_u32_e32 v62, vcc, s89, v100
	global_load_dwordx4 v[34:37], v[46:47], off offset:3072
	s_nop 0
	v_addc_co_u32_e32 v63, vcc, -1, v101, vcc
	global_load_dwordx4 v[54:57], v[62:63], off offset:2048
	v_add_co_u32_e32 v78, vcc, s94, v100
	s_mov_b32 s10, 0x3727c5ac
	s_nop 0
	v_addc_co_u32_e32 v79, vcc, -1, v101, vcc
	v_add_co_u32_e32 v94, vcc, s5, v100
	s_mov_b32 s5, 0x800000
	s_nop 0
	v_addc_co_u32_e32 v95, vcc, -1, v101, vcc
	global_load_dwordx4 v[70:73], v[78:79], off offset:2048
	global_load_dwordx4 v[86:89], v[94:95], off offset:2048
	s_waitcnt vmcnt(0) lgkmcnt(0)
	v_add_f32_e32 v42, v38, v39
	v_add_f32_e32 v42, v42, v40
	v_add_f32_e32 v50, v42, v41
	global_load_dwordx4 v[42:45], v[46:47], off offset:1024
	v_add_f32_e32 v0, v34, v35
	v_add_f32_e32 v0, v0, v36
	v_add_f32_e32 v58, v54, v55
	v_add_f32_e32 v58, v58, v56
	v_add_f32_e32 v66, v58, v57
	global_load_dwordx4 v[58:61], v[62:63], off offset:1024
	v_add_f32_e32 v0, v0, v37
	v_add_f32_e32 v74, v70, v71
	v_add_f32_e32 v74, v74, v72
	v_add_f32_e32 v82, v74, v73
	global_load_dwordx4 v[74:77], v[78:79], off offset:1024
	v_add_f32_e32 v90, v86, v87
	v_add_f32_e32 v90, v90, v88
	v_add_f32_e32 v106, v90, v89
	global_load_dwordx4 v[90:93], v[94:95], off offset:1024
	s_waitcnt vmcnt(0) lgkmcnt(0)
	v_add_f32_e32 v48, v42, v43
	v_add_f32_e32 v48, v48, v44
	v_add_f32_e32 v51, v48, v45
	global_load_dwordx4 v[46:49], v[46:47], off
	v_add_f32_e32 v64, v58, v59
	v_add_f32_e32 v64, v64, v60
	v_add_f32_e32 v67, v64, v61
	v_add_f32_e32 v80, v74, v75
	v_add_f32_e32 v80, v80, v76
	v_add_f32_e32 v83, v80, v77
	v_add_f32_e32 v96, v90, v91
	v_add_f32_e32 v96, v96, v92
	v_add_f32_e32 v107, v96, v93
	s_waitcnt vmcnt(0) lgkmcnt(0)
	v_add_f32_e32 v52, v46, v47
	v_add_f32_e32 v52, v52, v48
	v_add_f32_e32 v52, v52, v49
	v_add_f32_e32 v52, 0, v52
	v_add_f32_e32 v51, v52, v51
	v_add_f32_e32 v50, v51, v50
	v_add_f32_e32 v105, v50, v0
	global_load_dwordx4 v[50:53], v[62:63], off offset:3072
	s_waitcnt vmcnt(0) lgkmcnt(0)
	v_add_f32_e32 v0, v50, v51
	global_load_dwordx4 v[62:65], v[62:63], off
	v_add_f32_e32 v0, v0, v52
	v_add_f32_e32 v0, v0, v53
	s_waitcnt vmcnt(0) lgkmcnt(0)
	v_add_f32_e32 v68, v62, v63
	v_add_f32_e32 v68, v68, v64
	v_add_f32_e32 v68, v68, v65
	v_add_f32_e32 v68, 0, v68
	v_add_f32_e32 v67, v68, v67
	v_add_f32_e32 v66, v67, v66
	v_add_f32_e32 v104, v66, v0
	global_load_dwordx4 v[66:69], v[78:79], off offset:3072
	s_waitcnt vmcnt(0) lgkmcnt(0)
	v_add_f32_e32 v0, v66, v67
	global_load_dwordx4 v[78:81], v[78:79], off
	v_add_f32_e32 v0, v0, v68
	v_add_f32_e32 v0, v0, v69
	s_waitcnt vmcnt(0) lgkmcnt(0)
	v_add_f32_e32 v84, v78, v79
	v_add_f32_e32 v84, v84, v80
	v_add_f32_e32 v84, v84, v81
	v_add_f32_e32 v84, 0, v84
	v_add_f32_e32 v83, v84, v83
	v_add_f32_e32 v82, v83, v82
	v_add_f32_e32 v102, v82, v0
	global_load_dwordx4 v[82:85], v[94:95], off offset:3072
	s_waitcnt vmcnt(0) lgkmcnt(0)
	v_add_f32_e32 v0, v82, v83
	global_load_dwordx4 v[94:97], v[94:95], off
	v_add_f32_e32 v0, v0, v84
	v_add_f32_e32 v0, v0, v85
	s_waitcnt vmcnt(0) lgkmcnt(0)
	v_add_f32_e32 v108, v94, v95
	v_add_f32_e32 v108, v108, v96
	v_add_f32_e32 v108, v108, v97
	v_add_f32_e32 v108, 0, v108
	v_add_f32_e32 v107, v108, v107
	v_add_f32_e32 v106, v107, v106
	v_add_f32_e32 v0, v106, v0
	ds_swizzle_b32 v106, v0 offset:swizzle(SWAP,1)
	s_waitcnt lgkmcnt(0)
	v_add_f32_e32 v0, v0, v106
	ds_swizzle_b32 v106, v0 offset:swizzle(SWAP,2)
	s_waitcnt lgkmcnt(0)
	v_add_f32_e32 v0, v0, v106
	ds_swizzle_b32 v106, v0 offset:swizzle(SWAP,4)
	s_waitcnt lgkmcnt(0)
	v_add_f32_e32 v0, v0, v106
	ds_swizzle_b32 v106, v0 offset:swizzle(SWAP,8)
	s_waitcnt lgkmcnt(0)
	v_add_f32_e32 v0, v0, v106
	ds_swizzle_b32 v106, v0 offset:swizzle(SWAP,16)
	s_waitcnt lgkmcnt(0)
	v_add_f32_e32 v0, v0, v106
	v_mov_b32_e32 v106, v0
	s_nop 1
	v_permlane32_swap_b32_e32 v0, v106
	v_add_f32_e32 v0, v0, v106
	ds_swizzle_b32 v106, v102 offset:swizzle(SWAP,1)
	v_mul_f32_e32 v0, 0x3a800000, v0
	v_pk_add_f32 v[108:109], v[94:95], v[0:1] op_sel_hi:[1,0] neg_lo:[0,1] neg_hi:[0,1]
	v_pk_add_f32 v[94:95], v[92:93], v[0:1] op_sel_hi:[1,0] neg_lo:[0,1] neg_hi:[0,1]
	v_mov_b32_e32 v92, v109
	s_waitcnt lgkmcnt(0)
	v_add_f32_e32 v102, v102, v106
	ds_swizzle_b32 v106, v102 offset:swizzle(SWAP,2)
	s_waitcnt lgkmcnt(0)
	v_add_f32_e32 v102, v102, v106
	ds_swizzle_b32 v106, v102 offset:swizzle(SWAP,4)
	s_waitcnt lgkmcnt(0)
	v_add_f32_e32 v102, v102, v106
	ds_swizzle_b32 v106, v102 offset:swizzle(SWAP,8)
	s_waitcnt lgkmcnt(0)
	v_add_f32_e32 v102, v102, v106
	ds_swizzle_b32 v106, v102 offset:swizzle(SWAP,16)
	s_waitcnt lgkmcnt(0)
	v_add_f32_e32 v102, v102, v106
	v_mov_b32_e32 v106, v102
	s_nop 1
	v_permlane32_swap_b32_e32 v102, v106
	v_add_f32_e32 v102, v102, v106
	ds_swizzle_b32 v106, v104 offset:swizzle(SWAP,1)
	v_mul_f32_e32 v102, 0x3a800000, v102
	s_waitcnt lgkmcnt(0)
	v_add_f32_e32 v104, v104, v106
	ds_swizzle_b32 v106, v104 offset:swizzle(SWAP,2)
	s_waitcnt lgkmcnt(0)
	v_add_f32_e32 v104, v104, v106
	ds_swizzle_b32 v106, v104 offset:swizzle(SWAP,4)
	s_waitcnt lgkmcnt(0)
	v_add_f32_e32 v104, v104, v106
	ds_swizzle_b32 v106, v104 offset:swizzle(SWAP,8)
	s_waitcnt lgkmcnt(0)
	v_add_f32_e32 v104, v104, v106
	ds_swizzle_b32 v106, v104 offset:swizzle(SWAP,16)
	s_waitcnt lgkmcnt(0)
	v_add_f32_e32 v104, v104, v106
	v_mov_b32_e32 v106, v104
	s_nop 1
	v_permlane32_swap_b32_e32 v104, v106
	v_add_f32_e32 v104, v104, v106
	ds_swizzle_b32 v106, v105 offset:swizzle(SWAP,1)
	v_mul_f32_e32 v104, 0x3a800000, v104
	s_waitcnt lgkmcnt(0)
	v_add_f32_e32 v105, v105, v106
	ds_swizzle_b32 v106, v105 offset:swizzle(SWAP,2)
	s_waitcnt lgkmcnt(0)
	v_add_f32_e32 v105, v105, v106
	ds_swizzle_b32 v106, v105 offset:swizzle(SWAP,4)
	s_waitcnt lgkmcnt(0)
	v_add_f32_e32 v105, v105, v106
	ds_swizzle_b32 v106, v105 offset:swizzle(SWAP,8)
	s_waitcnt lgkmcnt(0)
	v_add_f32_e32 v105, v105, v106
	ds_swizzle_b32 v106, v105 offset:swizzle(SWAP,16)
	s_waitcnt lgkmcnt(0)
	v_add_f32_e32 v105, v105, v106
	v_mov_b32_e32 v106, v105
	s_nop 1
	v_permlane32_swap_b32_e32 v105, v106
	v_add_f32_e32 v105, v105, v106
	v_pk_add_f32 v[106:107], v[96:97], v[0:1] op_sel_hi:[1,0] neg_lo:[0,1] neg_hi:[0,1]
	v_pk_add_f32 v[96:97], v[90:91], v[0:1] op_sel_hi:[1,0] neg_lo:[0,1] neg_hi:[0,1]
	v_mov_b32_e32 v90, v108
	v_mov_b32_e32 v93, v97
	v_mov_b32_e32 v91, v96
	v_pk_mul_f32 v[92:93], v[92:93], v[92:93]
	v_mul_f32_e32 v110, 0x3a800000, v105
	v_pk_fma_f32 v[90:91], v[90:91], v[90:91], v[92:93]
	v_mov_b32_e32 v92, v106
	v_mov_b32_e32 v93, v94
	v_pk_fma_f32 v[90:91], v[92:93], v[92:93], v[90:91]
	v_mov_b32_e32 v92, v107
	v_mov_b32_e32 v93, v95
	v_pk_fma_f32 v[112:113], v[92:93], v[92:93], v[90:91]
	v_pk_add_f32 v[92:93], v[86:87], v[0:1] op_sel_hi:[1,0] neg_lo:[0,1] neg_hi:[0,1]
	v_pk_add_f32 v[90:91], v[88:89], v[0:1] op_sel_hi:[1,0] neg_lo:[0,1] neg_hi:[0,1]
	v_pk_add_f32 v[88:89], v[82:83], v[0:1] op_sel_hi:[1,0] neg_lo:[0,1] neg_hi:[0,1]
	v_pk_add_f32 v[86:87], v[84:85], v[0:1] op_sel_hi:[1,0] neg_lo:[0,1] neg_hi:[0,1]
	v_mov_b32_e32 v84, v89
	v_mov_b32_e32 v85, v93
	v_mov_b32_e32 v82, v88
	v_mov_b32_e32 v83, v92
	v_pk_mul_f32 v[84:85], v[84:85], v[84:85]
	s_nop 0
	v_pk_fma_f32 v[82:83], v[82:83], v[82:83], v[84:85]
	v_mov_b32_e32 v84, v86
	v_mov_b32_e32 v85, v90
	v_pk_fma_f32 v[82:83], v[84:85], v[84:85], v[82:83]
	v_mov_b32_e32 v84, v87
	v_mov_b32_e32 v85, v91
	v_pk_fma_f32 v[82:83], v[84:85], v[84:85], v[82:83]
	v_add_f32_e32 v84, v112, v113
	v_add_f32_e32 v83, v83, v84
	v_add_f32_e32 v105, v82, v83
	v_pk_add_f32 v[84:85], v[78:79], v[102:103] op_sel_hi:[1,0] neg_lo:[0,1] neg_hi:[0,1]
	v_pk_add_f32 v[82:83], v[80:81], v[102:103] op_sel_hi:[1,0] neg_lo:[0,1] neg_hi:[0,1]
	v_pk_add_f32 v[80:81], v[74:75], v[102:103] op_sel_hi:[1,0] neg_lo:[0,1] neg_hi:[0,1]
	v_pk_add_f32 v[78:79], v[76:77], v[102:103] op_sel_hi:[1,0] neg_lo:[0,1] neg_hi:[0,1]
	v_mov_b32_e32 v76, v85
	v_mov_b32_e32 v77, v81
	v_mov_b32_e32 v74, v84
	v_mov_b32_e32 v75, v80
	v_pk_mul_f32 v[76:77], v[76:77], v[76:77]
	s_nop 0
	v_pk_fma_f32 v[74:75], v[74:75], v[74:75], v[76:77]
	v_mov_b32_e32 v76, v82
	v_mov_b32_e32 v77, v78
	v_pk_fma_f32 v[74:75], v[76:77], v[76:77], v[74:75]
	v_mov_b32_e32 v76, v83
	v_mov_b32_e32 v77, v79
	v_pk_fma_f32 v[112:113], v[76:77], v[76:77], v[74:75]
	v_pk_add_f32 v[76:77], v[70:71], v[102:103] op_sel_hi:[1,0] neg_lo:[0,1] neg_hi:[0,1]
	v_pk_add_f32 v[74:75], v[72:73], v[102:103] op_sel_hi:[1,0] neg_lo:[0,1] neg_hi:[0,1]
	v_pk_add_f32 v[72:73], v[66:67], v[102:103] op_sel_hi:[1,0] neg_lo:[0,1] neg_hi:[0,1]
	v_pk_add_f32 v[70:71], v[68:69], v[102:103] op_sel_hi:[1,0] neg_lo:[0,1] neg_hi:[0,1]
	v_mov_b32_e32 v68, v73
	v_mov_b32_e32 v69, v77
	v_mov_b32_e32 v66, v72
	v_mov_b32_e32 v67, v76
	v_pk_mul_f32 v[68:69], v[68:69], v[68:69]
	s_nop 0
	v_pk_fma_f32 v[66:67], v[66:67], v[66:67], v[68:69]
	v_mov_b32_e32 v68, v70
	v_mov_b32_e32 v69, v74
	v_pk_fma_f32 v[66:67], v[68:69], v[68:69], v[66:67]
	v_mov_b32_e32 v68, v71
	v_mov_b32_e32 v69, v75
	v_pk_fma_f32 v[66:67], v[68:69], v[68:69], v[66:67]
	v_add_f32_e32 v68, v112, v113
	v_add_f32_e32 v67, v67, v68
	v_add_f32_e32 v111, v66, v67
	v_pk_add_f32 v[68:69], v[62:63], v[104:105] op_sel_hi:[1,0] neg_lo:[0,1] neg_hi:[0,1]
	v_pk_add_f32 v[66:67], v[64:65], v[104:105] op_sel_hi:[1,0] neg_lo:[0,1] neg_hi:[0,1]
	v_pk_add_f32 v[64:65], v[58:59], v[104:105] op_sel_hi:[1,0] neg_lo:[0,1] neg_hi:[0,1]
	v_pk_add_f32 v[62:63], v[60:61], v[104:105] op_sel_hi:[1,0] neg_lo:[0,1] neg_hi:[0,1]
	v_mov_b32_e32 v60, v69
	v_mov_b32_e32 v61, v65
	v_mov_b32_e32 v58, v68
	v_mov_b32_e32 v59, v64
	v_pk_mul_f32 v[60:61], v[60:61], v[60:61]
	s_nop 0
	v_pk_fma_f32 v[58:59], v[58:59], v[58:59], v[60:61]
	v_mov_b32_e32 v60, v66
	v_mov_b32_e32 v61, v62
	v_pk_fma_f32 v[58:59], v[60:61], v[60:61], v[58:59]
	v_mov_b32_e32 v60, v67
	v_mov_b32_e32 v61, v63
	v_pk_fma_f32 v[112:113], v[60:61], v[60:61], v[58:59]
	v_pk_add_f32 v[60:61], v[54:55], v[104:105] op_sel_hi:[1,0] neg_lo:[0,1] neg_hi:[0,1]
	v_pk_add_f32 v[58:59], v[56:57], v[104:105] op_sel_hi:[1,0] neg_lo:[0,1] neg_hi:[0,1]
	v_pk_add_f32 v[56:57], v[50:51], v[104:105] op_sel_hi:[1,0] neg_lo:[0,1] neg_hi:[0,1]
	v_pk_add_f32 v[54:55], v[52:53], v[104:105] op_sel_hi:[1,0] neg_lo:[0,1] neg_hi:[0,1]
	v_mov_b32_e32 v52, v57
	v_mov_b32_e32 v53, v61
	v_mov_b32_e32 v50, v56
	v_mov_b32_e32 v51, v60
	v_pk_mul_f32 v[52:53], v[52:53], v[52:53]
	s_nop 0
	v_pk_fma_f32 v[50:51], v[50:51], v[50:51], v[52:53]
	v_mov_b32_e32 v52, v54
	v_mov_b32_e32 v53, v58
	v_pk_fma_f32 v[50:51], v[52:53], v[52:53], v[50:51]
	v_mov_b32_e32 v52, v55
	v_mov_b32_e32 v53, v59
	v_pk_fma_f32 v[50:51], v[52:53], v[52:53], v[50:51]
	v_add_f32_e32 v52, v112, v113
	v_add_f32_e32 v51, v51, v52
	v_add_f32_e32 v114, v50, v51
	v_pk_add_f32 v[52:53], v[46:47], v[110:111] op_sel_hi:[1,0] neg_lo:[0,1] neg_hi:[0,1]
	v_pk_add_f32 v[50:51], v[48:49], v[110:111] op_sel_hi:[1,0] neg_lo:[0,1] neg_hi:[0,1]
	v_pk_add_f32 v[48:49], v[42:43], v[110:111] op_sel_hi:[1,0] neg_lo:[0,1] neg_hi:[0,1]
	v_pk_add_f32 v[46:47], v[44:45], v[110:111] op_sel_hi:[1,0] neg_lo:[0,1] neg_hi:[0,1]
	v_mov_b32_e32 v44, v53
	v_mov_b32_e32 v45, v49
	v_mov_b32_e32 v42, v52
	v_mov_b32_e32 v43, v48
	v_pk_mul_f32 v[44:45], v[44:45], v[44:45]
	s_nop 0
	v_pk_fma_f32 v[42:43], v[42:43], v[42:43], v[44:45]
	v_mov_b32_e32 v44, v50
	v_mov_b32_e32 v45, v46
	v_pk_fma_f32 v[42:43], v[44:45], v[44:45], v[42:43]
	v_mov_b32_e32 v44, v51
	v_mov_b32_e32 v45, v47
	v_pk_fma_f32 v[112:113], v[44:45], v[44:45], v[42:43]
	v_pk_add_f32 v[44:45], v[38:39], v[110:111] op_sel_hi:[1,0] neg_lo:[0,1] neg_hi:[0,1]
	v_pk_add_f32 v[42:43], v[40:41], v[110:111] op_sel_hi:[1,0] neg_lo:[0,1] neg_hi:[0,1]
	v_pk_add_f32 v[40:41], v[34:35], v[110:111] op_sel_hi:[1,0] neg_lo:[0,1] neg_hi:[0,1]
	v_pk_add_f32 v[38:39], v[36:37], v[110:111] op_sel_hi:[1,0] neg_lo:[0,1] neg_hi:[0,1]
	v_mov_b32_e32 v36, v41
	v_mov_b32_e32 v37, v45
	v_mov_b32_e32 v34, v40
	v_mov_b32_e32 v35, v44
	v_pk_mul_f32 v[36:37], v[36:37], v[36:37]
	s_nop 0
	v_pk_fma_f32 v[34:35], v[34:35], v[34:35], v[36:37]
	v_mov_b32_e32 v36, v38
	v_mov_b32_e32 v37, v42
	v_pk_fma_f32 v[34:35], v[36:37], v[36:37], v[34:35]
	v_mov_b32_e32 v36, v39
	v_mov_b32_e32 v37, v43
	v_pk_fma_f32 v[34:35], v[36:37], v[36:37], v[34:35]
	v_add_f32_e32 v36, v112, v113
	v_add_f32_e32 v35, v35, v36
	v_add_f32_e32 v113, v34, v35
	ds_swizzle_b32 v34, v105 offset:swizzle(SWAP,1)
	s_waitcnt lgkmcnt(0)
	v_add_f32_e32 v34, v105, v34
	ds_swizzle_b32 v35, v34 offset:swizzle(SWAP,2)
	s_waitcnt lgkmcnt(0)
	v_add_f32_e32 v34, v34, v35
	ds_swizzle_b32 v35, v34 offset:swizzle(SWAP,4)
	s_waitcnt lgkmcnt(0)
	v_add_f32_e32 v34, v34, v35
	ds_swizzle_b32 v35, v34 offset:swizzle(SWAP,8)
	s_waitcnt lgkmcnt(0)
	v_add_f32_e32 v34, v34, v35
	ds_swizzle_b32 v35, v34 offset:swizzle(SWAP,16)
	s_waitcnt lgkmcnt(0)
	v_add_f32_e32 v35, v34, v35
	ds_swizzle_b32 v34, v111 offset:swizzle(SWAP,1)
	v_mov_b32_e32 v37, v35
	s_waitcnt lgkmcnt(0)
	v_add_f32_e32 v34, v111, v34
	ds_swizzle_b32 v36, v34 offset:swizzle(SWAP,2)
	v_permlane32_swap_b32_e32 v35, v37
	s_waitcnt lgkmcnt(0)
	v_add_f32_e32 v34, v34, v36
	ds_swizzle_b32 v36, v34 offset:swizzle(SWAP,4)
	s_waitcnt lgkmcnt(0)
	v_add_f32_e32 v34, v34, v36
	ds_swizzle_b32 v36, v34 offset:swizzle(SWAP,8)
	s_waitcnt lgkmcnt(0)
	v_add_f32_e32 v34, v34, v36
	ds_swizzle_b32 v36, v34 offset:swizzle(SWAP,16)
	s_waitcnt lgkmcnt(0)
	v_add_f32_e32 v34, v34, v36
	v_mov_b32_e32 v36, v34
	s_nop 1
	v_permlane32_swap_b32_e32 v34, v36
	v_pk_add_f32 v[36:37], v[34:35], v[36:37]
	v_mov_b64_e32 v[34:35], s[10:11]
	s_mov_b32 s10, 0x3a800000
	v_pk_fma_f32 v[36:37], v[36:37], s[10:11], v[34:35] op_sel_hi:[1,0,0]
	s_nop 0
	v_mul_f32_e32 v105, 0x4b800000, v37
	v_cmp_gt_f32_e64 s[48:49], s5, v37
	v_cmp_gt_f32_e32 vcc, s5, v36
	s_nop 0
	v_cndmask_b32_e64 v37, v37, v105, s[48:49]
	v_rsq_f32_e32 v37, v37
	s_nop 0
	v_mul_f32_e32 v105, 0x45800000, v37
	v_cndmask_b32_e64 v116, v37, v105, s[48:49]
	v_mul_f32_e32 v37, 0x4b800000, v36
	v_cndmask_b32_e32 v36, v36, v37, vcc
	v_rsq_f32_e32 v36, v36
	s_nop 0
	v_mul_f32_e32 v37, 0x45800000, v36
	v_cndmask_b32_e32 v112, v36, v37, vcc
	ds_swizzle_b32 v36, v114 offset:swizzle(SWAP,1)
	s_waitcnt lgkmcnt(0)
	v_add_f32_e32 v36, v114, v36
	ds_swizzle_b32 v37, v36 offset:swizzle(SWAP,2)
	s_waitcnt lgkmcnt(0)
	v_add_f32_e32 v36, v36, v37
	ds_swizzle_b32 v37, v36 offset:swizzle(SWAP,4)
	s_waitcnt lgkmcnt(0)
	v_add_f32_e32 v36, v36, v37
	ds_swizzle_b32 v37, v36 offset:swizzle(SWAP,8)
	s_waitcnt lgkmcnt(0)
	v_add_f32_e32 v36, v36, v37
	ds_swizzle_b32 v37, v36 offset:swizzle(SWAP,16)
	s_waitcnt lgkmcnt(0)
	v_add_f32_e32 v37, v36, v37
	ds_swizzle_b32 v36, v113 offset:swizzle(SWAP,1)
	v_mov_b32_e32 v115, v37
	s_waitcnt lgkmcnt(0)
	v_add_f32_e32 v36, v113, v36
	ds_swizzle_b32 v105, v36 offset:swizzle(SWAP,2)
	v_permlane32_swap_b32_e32 v37, v115
	s_waitcnt lgkmcnt(0)
	v_add_f32_e32 v36, v36, v105
	ds_swizzle_b32 v105, v36 offset:swizzle(SWAP,4)
	s_waitcnt lgkmcnt(0)
	v_add_f32_e32 v36, v36, v105
	ds_swizzle_b32 v105, v36 offset:swizzle(SWAP,8)
	s_waitcnt lgkmcnt(0)
	v_add_f32_e32 v36, v36, v105
	ds_swizzle_b32 v105, v36 offset:swizzle(SWAP,16)
	s_waitcnt lgkmcnt(0)
	v_add_f32_e32 v36, v36, v105
	v_mov_b32_e32 v114, v36
	s_nop 1
	v_permlane32_swap_b32_e32 v36, v114
	v_pk_add_f32 v[36:37], v[36:37], v[114:115]
	s_nop 0
	v_pk_fma_f32 v[34:35], v[36:37], s[10:11], v[34:35] op_sel_hi:[1,0,0]
	s_nop 0
	v_mul_f32_e32 v36, 0x4b800000, v35
	v_cmp_gt_f32_e64 s[48:49], s5, v35
	v_cmp_gt_f32_e32 vcc, s5, v34
	s_nop 0
	v_cndmask_b32_e64 v35, v35, v36, s[48:49]
	v_rsq_f32_e32 v35, v35
	s_nop 0
	v_mul_f32_e32 v36, 0x45800000, v35
	v_cndmask_b32_e64 v118, v35, v36, s[48:49]
	v_mul_f32_e32 v35, 0x4b800000, v34
	v_cndmask_b32_e32 v34, v34, v35, vcc
	v_rsq_f32_e32 v34, v34
	s_nop 0
	v_mul_f32_e32 v35, 0x45800000, v34
	v_cndmask_b32_e32 v114, v34, v35, vcc
	s_and_saveexec_b64 s[48:49], s[40:41]
	s_cbranch_execz .LBB0_727
	v_cndmask_b32_e64 v34, v110, v104, s[46:47]
	v_cndmask_b32_e64 v34, v34, v102, s[44:45]
	v_cndmask_b32_e64 v34, v34, v0, s[42:43]
	v_cndmask_b32_e64 v0, v114, v118, s[46:47]
	v_add_u32_e32 v36, s4, v103
	v_cndmask_b32_e64 v0, v0, v112, s[44:45]
	v_ashrrev_i32_e32 v37, 31, v36
	v_cndmask_b32_e64 v35, v0, v116, s[42:43]
	v_lshl_add_u64 v[36:37], v[36:37], 3, s[8:9]
	global_store_dwordx2 v[36:37], v[34:35], off
.LBB0_727:
	s_or_b64 exec, exec, s[48:49]
	v_pk_mul_f32 v[34:35], v[108:109], v[116:117] op_sel_hi:[1,0]
	v_pk_mul_f32 v[36:37], v[106:107], v[116:117] op_sel_hi:[1,0]
	v_cndmask_b32_e64 v0, 0, 1, s[14:15]
	v_pk_fma_f32 v[34:35], v[2:3], v[34:35], v[10:11]
	v_cmp_ne_u32_e64 s[48:49], 1, v0
	s_andn2_b64 vcc, exec, s[14:15]
	v_pk_fma_f32 v[36:37], v[4:5], v[36:37], v[12:13]
	s_cbranch_vccnz .LBB0_729
	s_movk_i32 s56, 0xc3f8
	s_mov_b32 s57, -1
	v_lshl_add_u64 v[104:105], v[100:101], 0, s[56:57]
	global_store_dwordx4 v[104:105], v[34:37], off
.LBB0_729:
	s_nop 1
	v_cvt_pk_bf16_f32 v34, v34, v35
	v_cvt_pk_bf16_f32 v35, v36, v37
	v_add_co_u32_e32 v36, vcc, 0xffffe1fc, v98
	v_mov_b32_e32 v117, v116
	s_nop 0
	v_addc_co_u32_e32 v37, vcc, -1, v99, vcc
	global_store_dwordx2 v[36:37], v[34:35], off
	v_pk_mul_f32 v[34:35], v[96:97], v[116:117]
	v_pk_mul_f32 v[36:37], v[94:95], v[116:117]
	v_pk_fma_f32 v[34:35], v[6:7], v[34:35], v[14:15]
	s_and_b64 vcc, exec, s[48:49]
	v_pk_fma_f32 v[36:37], v[8:9], v[36:37], v[16:17]
	s_cbranch_vccnz .LBB0_731
	s_movk_i32 s56, 0xc7f8
	s_mov_b32 s57, -1
	v_lshl_add_u64 v[94:95], v[100:101], 0, s[56:57]
	global_store_dwordx4 v[94:95], v[34:37], off
.LBB0_731:
	s_nop 1
	v_cvt_pk_bf16_f32 v34, v34, v35
	v_cvt_pk_bf16_f32 v35, v36, v37
	v_add_co_u32_e32 v36, vcc, 0xffffe3fc, v98
	s_nop 1
	v_addc_co_u32_e32 v37, vcc, -1, v99, vcc
	global_store_dwordx2 v[36:37], v[34:35], off
	v_pk_mul_f32 v[34:35], v[92:93], v[116:117]
	v_pk_mul_f32 v[36:37], v[90:91], v[116:117]
	v_pk_fma_f32 v[34:35], v[18:19], v[34:35], v[26:27]
	s_and_b64 vcc, exec, s[48:49]
	v_pk_fma_f32 v[36:37], v[20:21], v[36:37], v[28:29]
	s_cbranch_vccnz .LBB0_733
	s_movk_i32 s56, 0xcbf8
	s_mov_b32 s57, -1
	v_lshl_add_u64 v[90:91], v[100:101], 0, s[56:57]
	global_store_dwordx4 v[90:91], v[34:37], off
.LBB0_733:
	s_nop 1
	v_cvt_pk_bf16_f32 v34, v34, v35
	v_cvt_pk_bf16_f32 v35, v36, v37
	v_add_co_u32_e32 v36, vcc, 0xffffe5fc, v98
	s_nop 1
	v_addc_co_u32_e32 v37, vcc, -1, v99, vcc
	global_store_dwordx2 v[36:37], v[34:35], off
	v_pk_mul_f32 v[34:35], v[88:89], v[116:117]
	v_pk_mul_f32 v[36:37], v[86:87], v[116:117]
	v_pk_fma_f32 v[34:35], v[22:23], v[34:35], v[30:31]
	s_and_b64 vcc, exec, s[48:49]
	v_pk_fma_f32 v[36:37], v[24:25], v[36:37], v[32:33]
	s_cbranch_vccnz .LBB0_735
	s_movk_i32 s56, 0xcff8
	s_mov_b32 s57, -1
	v_lshl_add_u64 v[86:87], v[100:101], 0, s[56:57]
	global_store_dwordx4 v[86:87], v[34:37], off
.LBB0_735:
	s_nop 1
	v_cvt_pk_bf16_f32 v34, v34, v35
	v_cvt_pk_bf16_f32 v35, v36, v37
	v_add_co_u32_e32 v36, vcc, 0xffffe7fc, v98
	s_nop 1
	v_addc_co_u32_e32 v37, vcc, -1, v99, vcc
	global_store_dwordx2 v[36:37], v[34:35], off
	v_pk_mul_f32 v[34:35], v[84:85], v[112:113] op_sel_hi:[1,0]
	v_pk_mul_f32 v[36:37], v[82:83], v[112:113] op_sel_hi:[1,0]
	v_pk_fma_f32 v[34:35], v[2:3], v[34:35], v[10:11]
	s_and_b64 vcc, exec, s[48:49]
	v_pk_fma_f32 v[36:37], v[4:5], v[36:37], v[12:13]
	s_cbranch_vccnz .LBB0_737
	s_movk_i32 s56, 0xd3f8
	s_mov_b32 s57, -1
	v_lshl_add_u64 v[82:83], v[100:101], 0, s[56:57]
	global_store_dwordx4 v[82:83], v[34:37], off
.LBB0_737:
	s_nop 1
	v_cvt_pk_bf16_f32 v34, v34, v35
	v_cvt_pk_bf16_f32 v35, v36, v37
	v_add_co_u32_e32 v36, vcc, 0xffffe9fc, v98
	v_mov_b32_e32 v113, v112
	s_nop 0
	v_addc_co_u32_e32 v37, vcc, -1, v99, vcc
	global_store_dwordx2 v[36:37], v[34:35], off
	v_pk_mul_f32 v[34:35], v[80:81], v[112:113]
	v_pk_mul_f32 v[36:37], v[78:79], v[112:113]
	v_pk_fma_f32 v[34:35], v[6:7], v[34:35], v[14:15]
	s_and_b64 vcc, exec, s[48:49]
	v_pk_fma_f32 v[36:37], v[8:9], v[36:37], v[16:17]
	s_cbranch_vccnz .LBB0_739
	s_movk_i32 s56, 0xd7f8
	s_mov_b32 s57, -1
	v_lshl_add_u64 v[78:79], v[100:101], 0, s[56:57]
	global_store_dwordx4 v[78:79], v[34:37], off
.LBB0_739:
	s_nop 1
	v_cvt_pk_bf16_f32 v34, v34, v35
	v_cvt_pk_bf16_f32 v35, v36, v37
	v_add_co_u32_e32 v36, vcc, 0xffffebfc, v98
	s_nop 1
	v_addc_co_u32_e32 v37, vcc, -1, v99, vcc
	global_store_dwordx2 v[36:37], v[34:35], off
	v_pk_mul_f32 v[34:35], v[76:77], v[112:113]
	v_pk_mul_f32 v[36:37], v[74:75], v[112:113]
	v_pk_fma_f32 v[34:35], v[18:19], v[34:35], v[26:27]
	s_and_b64 vcc, exec, s[48:49]
	v_pk_fma_f32 v[36:37], v[20:21], v[36:37], v[28:29]
	s_cbranch_vccnz .LBB0_741
	s_movk_i32 s56, 0xdbf8
	s_mov_b32 s57, -1
	v_lshl_add_u64 v[74:75], v[100:101], 0, s[56:57]
	global_store_dwordx4 v[74:75], v[34:37], off
.LBB0_741:
	s_nop 1
	v_cvt_pk_bf16_f32 v34, v34, v35
	v_cvt_pk_bf16_f32 v35, v36, v37
	v_add_co_u32_e32 v36, vcc, 0xffffedfc, v98
	s_nop 1
	v_addc_co_u32_e32 v37, vcc, -1, v99, vcc
	global_store_dwordx2 v[36:37], v[34:35], off
	v_pk_mul_f32 v[34:35], v[72:73], v[112:113]
	v_pk_mul_f32 v[36:37], v[70:71], v[112:113]
	v_pk_fma_f32 v[34:35], v[22:23], v[34:35], v[30:31]
	s_and_b64 vcc, exec, s[48:49]
	v_pk_fma_f32 v[36:37], v[24:25], v[36:37], v[32:33]
	s_cbranch_vccnz .LBB0_743
	s_movk_i32 s56, 0xdff8
	s_mov_b32 s57, -1
	v_lshl_add_u64 v[70:71], v[100:101], 0, s[56:57]
	global_store_dwordx4 v[70:71], v[34:37], off
.LBB0_743:
	s_nop 1
	v_cvt_pk_bf16_f32 v34, v34, v35
	v_cvt_pk_bf16_f32 v35, v36, v37
	v_add_co_u32_e32 v36, vcc, 0xffffeffc, v98
	s_nop 1
	v_addc_co_u32_e32 v37, vcc, -1, v99, vcc
	global_store_dwordx2 v[36:37], v[34:35], off
	v_pk_mul_f32 v[34:35], v[68:69], v[118:119] op_sel_hi:[1,0]
	v_pk_mul_f32 v[36:37], v[66:67], v[118:119] op_sel_hi:[1,0]
	v_pk_fma_f32 v[34:35], v[2:3], v[34:35], v[10:11]
	s_and_b64 vcc, exec, s[48:49]
	v_pk_fma_f32 v[36:37], v[4:5], v[36:37], v[12:13]
	s_cbranch_vccnz .LBB0_745
	s_movk_i32 s56, 0xe3f8
	s_mov_b32 s57, -1
	v_lshl_add_u64 v[66:67], v[100:101], 0, s[56:57]
	global_store_dwordx4 v[66:67], v[34:37], off
.LBB0_745:
	s_nop 1
	v_cvt_pk_bf16_f32 v34, v34, v35
	v_cvt_pk_bf16_f32 v35, v36, v37
	v_add_co_u32_e32 v36, vcc, 0xfffff1fc, v98
	v_mov_b32_e32 v119, v118
	s_nop 0
	v_addc_co_u32_e32 v37, vcc, -1, v99, vcc
	global_store_dwordx2 v[36:37], v[34:35], off
	v_pk_mul_f32 v[34:35], v[64:65], v[118:119]
	v_pk_mul_f32 v[36:37], v[62:63], v[118:119]
	v_pk_fma_f32 v[34:35], v[6:7], v[34:35], v[14:15]
	s_and_b64 vcc, exec, s[48:49]
	v_pk_fma_f32 v[36:37], v[8:9], v[36:37], v[16:17]
	s_cbranch_vccnz .LBB0_747
	s_movk_i32 s56, 0xe7f8
	s_mov_b32 s57, -1
	v_lshl_add_u64 v[62:63], v[100:101], 0, s[56:57]
	global_store_dwordx4 v[62:63], v[34:37], off
.LBB0_747:
	s_nop 1
	v_cvt_pk_bf16_f32 v34, v34, v35
	v_cvt_pk_bf16_f32 v35, v36, v37
	v_add_co_u32_e32 v36, vcc, 0xfffff3fc, v98
	s_nop 1
	v_addc_co_u32_e32 v37, vcc, -1, v99, vcc
	global_store_dwordx2 v[36:37], v[34:35], off
	v_pk_mul_f32 v[34:35], v[60:61], v[118:119]
	v_pk_mul_f32 v[36:37], v[58:59], v[118:119]
	v_pk_fma_f32 v[34:35], v[18:19], v[34:35], v[26:27]
	s_and_b64 vcc, exec, s[48:49]
	v_pk_fma_f32 v[36:37], v[20:21], v[36:37], v[28:29]
	s_cbranch_vccnz .LBB0_749
	s_movk_i32 s56, 0xebf8
	s_mov_b32 s57, -1
	v_lshl_add_u64 v[58:59], v[100:101], 0, s[56:57]
	global_store_dwordx4 v[58:59], v[34:37], off
.LBB0_749:
	s_nop 1
	v_cvt_pk_bf16_f32 v34, v34, v35
	v_cvt_pk_bf16_f32 v35, v36, v37
	v_add_co_u32_e32 v36, vcc, 0xfffff5fc, v98
	s_nop 1
	v_addc_co_u32_e32 v37, vcc, -1, v99, vcc
	global_store_dwordx2 v[36:37], v[34:35], off
	v_pk_mul_f32 v[34:35], v[56:57], v[118:119]
	v_pk_mul_f32 v[36:37], v[54:55], v[118:119]
	v_pk_fma_f32 v[34:35], v[22:23], v[34:35], v[30:31]
	s_and_b64 vcc, exec, s[48:49]
	v_pk_fma_f32 v[36:37], v[24:25], v[36:37], v[32:33]
	s_cbranch_vccnz .LBB0_751
	s_movk_i32 s56, 0xeff8
	s_mov_b32 s57, -1
	v_lshl_add_u64 v[54:55], v[100:101], 0, s[56:57]
	global_store_dwordx4 v[54:55], v[34:37], off
.LBB0_751:
	s_nop 1
	v_cvt_pk_bf16_f32 v34, v34, v35
	v_cvt_pk_bf16_f32 v35, v36, v37
	v_add_co_u32_e32 v36, vcc, 0xfffff7fc, v98
	s_nop 1
	v_addc_co_u32_e32 v37, vcc, -1, v99, vcc
	global_store_dwordx2 v[36:37], v[34:35], off
	v_pk_mul_f32 v[34:35], v[52:53], v[114:115] op_sel_hi:[1,0]
	v_pk_mul_f32 v[36:37], v[50:51], v[114:115] op_sel_hi:[1,0]
	v_pk_fma_f32 v[34:35], v[2:3], v[34:35], v[10:11]
	s_and_b64 vcc, exec, s[48:49]
	v_pk_fma_f32 v[36:37], v[4:5], v[36:37], v[12:13]
	s_cbranch_vccnz .LBB0_753
	s_movk_i32 s56, 0xf3f8
	s_mov_b32 s57, -1
	v_lshl_add_u64 v[50:51], v[100:101], 0, s[56:57]
	global_store_dwordx4 v[50:51], v[34:37], off
.LBB0_753:
	s_nop 1
	v_cvt_pk_bf16_f32 v34, v34, v35
	v_cvt_pk_bf16_f32 v35, v36, v37
	v_add_co_u32_e32 v36, vcc, 0xfffff9fc, v98
	v_mov_b32_e32 v115, v114
	s_nop 0
	v_addc_co_u32_e32 v37, vcc, -1, v99, vcc
	global_store_dwordx2 v[36:37], v[34:35], off
	v_pk_mul_f32 v[34:35], v[48:49], v[114:115]
	v_pk_mul_f32 v[36:37], v[46:47], v[114:115]
	v_pk_fma_f32 v[34:35], v[6:7], v[34:35], v[14:15]
	s_and_b64 vcc, exec, s[48:49]
	v_pk_fma_f32 v[36:37], v[8:9], v[36:37], v[16:17]
	s_cbranch_vccnz .LBB0_755
	s_movk_i32 s56, 0xf7f8
	s_mov_b32 s57, -1
	v_lshl_add_u64 v[46:47], v[100:101], 0, s[56:57]
	global_store_dwordx4 v[46:47], v[34:37], off
.LBB0_755:
	s_nop 1
	v_cvt_pk_bf16_f32 v34, v34, v35
	v_cvt_pk_bf16_f32 v35, v36, v37
	v_add_co_u32_e32 v36, vcc, 0xfffffbfc, v98
	s_nop 1
	v_addc_co_u32_e32 v37, vcc, -1, v99, vcc
	global_store_dwordx2 v[36:37], v[34:35], off
	v_pk_mul_f32 v[34:35], v[44:45], v[114:115]
	v_pk_mul_f32 v[36:37], v[42:43], v[114:115]
	v_pk_fma_f32 v[34:35], v[18:19], v[34:35], v[26:27]
	s_and_b64 vcc, exec, s[48:49]
	v_pk_fma_f32 v[36:37], v[20:21], v[36:37], v[28:29]
	s_cbranch_vccnz .LBB0_757
	s_movk_i32 s56, 0xfbf8
	s_mov_b32 s57, -1
	v_lshl_add_u64 v[42:43], v[100:101], 0, s[56:57]
	global_store_dwordx4 v[42:43], v[34:37], off
.LBB0_757:
	s_nop 1
	v_cvt_pk_bf16_f32 v34, v34, v35
	v_cvt_pk_bf16_f32 v35, v36, v37
	v_add_co_u32_e32 v36, vcc, 0xfffffdfc, v98
	s_nop 1
	v_addc_co_u32_e32 v37, vcc, -1, v99, vcc
	global_store_dwordx2 v[36:37], v[34:35], off
	v_pk_mul_f32 v[34:35], v[40:41], v[114:115]
	v_pk_mul_f32 v[36:37], v[38:39], v[114:115]
	v_pk_fma_f32 v[34:35], v[22:23], v[34:35], v[30:31]
	s_and_b64 vcc, exec, s[48:49]
	v_pk_fma_f32 v[36:37], v[24:25], v[36:37], v[32:33]
	s_cbranch_vccnz .LBB0_724
	v_lshl_add_u64 v[38:39], v[100:101], 0, -8
	global_store_dwordx4 v[38:39], v[34:37], off
	s_branch .LBB0_724

.LBB0_764:
	v_mov_b32_e32 v0, v176
	s_lshl_b32 s9, s29, 3
	s_nop 0
	v_permlane32_swap_b32_e32 v176, v0
	v_add_f32_e32 v0, v176, v0
	s_waitcnt vmcnt(0)
	v_div_scale_f32 v4, s[14:15], v0, v0, 1.0
	v_rcp_f32_e32 v5, v4
	s_and_b32 s9, s9, 0xfffff000
	v_or_b32_e32 v2, s9, v171
	v_ashrrev_i32_e32 v3, 31, v2
	s_waitcnt vmcnt(0)
	v_fma_f32 v6, -v4, v5, 1.0
	v_fmac_f32_e32 v5, v6, v5
	v_div_scale_f32 v6, vcc, 1.0, v0, 1.0
	v_mul_f32_e32 v7, v6, v5
	v_lshlrev_b64 v[2:3], 11, v[2:3]
	s_lshl_b32 s8, s8, 7
	v_fma_f32 v8, -v4, v7, v6
	v_lshl_add_u64 v[2:3], s[58:59], 0, v[2:3]
	s_and_b32 s10, s8, 0x180
	v_fmac_f32_e32 v7, v8, v5
	v_lshl_add_u64 v[2:3], v[2:3], 0, s[10:11]
	v_fma_f32 v4, -v4, v7, v6
	v_mov_b32_e32 v171, v1
	v_div_fmas_f32 v4, v4, v5, v7
	v_lshl_add_u64 v[2:3], v[2:3], 0, v[170:171]
	s_mov_b64 s[8:9], 0xa500600
	v_div_fixup_f32 v0, v4, v0, 1.0
	v_lshl_add_u64 v[4:5], v[2:3], 0, s[8:9]
	s_mov_b32 s8, 0xa500000
	v_mul_f32_e32 v6, v32, v0
	v_mul_f32_e32 v8, v33, v0
	v_mul_f32_e32 v7, v34, v0
	v_mul_f32_e32 v9, v35, v0
	v_add_co_u32_e32 v2, vcc, s8, v2
	v_cvt_pk_bf16_f32 v7, v7, v9
	v_cvt_pk_bf16_f32 v6, v6, v8
	v_addc_co_u32_e32 v3, vcc, 0, v3, vcc
	global_store_dwordx2 v[2:3], v[6:7], off offset:1536
	v_mul_f32_e32 v2, v36, v0
	v_mul_f32_e32 v6, v37, v0
	v_mul_f32_e32 v3, v38, v0
	v_mul_f32_e32 v7, v39, v0
	v_cvt_pk_bf16_f32 v3, v3, v7
	v_cvt_pk_bf16_f32 v2, v2, v6
	global_store_dwordx2 v[4:5], v[2:3], off offset:16
	v_mul_f32_e32 v2, v40, v0
	v_mul_f32_e32 v6, v41, v0
	v_mul_f32_e32 v3, v42, v0
	v_mul_f32_e32 v7, v43, v0
	v_cvt_pk_bf16_f32 v3, v3, v7
	v_cvt_pk_bf16_f32 v2, v2, v6
	global_store_dwordx2 v[4:5], v[2:3], off offset:32
	v_mul_f32_e32 v2, v44, v0
	v_mul_f32_e32 v6, v45, v0
	v_mul_f32_e32 v3, v46, v0
	v_mul_f32_e32 v7, v47, v0
	v_cvt_pk_bf16_f32 v3, v3, v7
	v_cvt_pk_bf16_f32 v2, v2, v6
	global_store_dwordx2 v[4:5], v[2:3], off offset:48
	v_mul_f32_e32 v2, v16, v0
	v_mul_f32_e32 v6, v17, v0
	v_mul_f32_e32 v3, v18, v0
	v_mul_f32_e32 v7, v19, v0
	v_cvt_pk_bf16_f32 v3, v3, v7
	v_cvt_pk_bf16_f32 v2, v2, v6
	global_store_dwordx2 v[4:5], v[2:3], off offset:64
	v_mul_f32_e32 v2, v20, v0
	v_mul_f32_e32 v6, v21, v0
	v_mul_f32_e32 v3, v22, v0
	v_mul_f32_e32 v7, v23, v0
	v_cvt_pk_bf16_f32 v3, v3, v7
	v_cvt_pk_bf16_f32 v2, v2, v6
	global_store_dwordx2 v[4:5], v[2:3], off offset:80
	v_mul_f32_e32 v2, v24, v0
	v_mul_f32_e32 v6, v25, v0
	v_mul_f32_e32 v3, v26, v0
	v_mul_f32_e32 v7, v27, v0
	v_cvt_pk_bf16_f32 v3, v3, v7
	v_cvt_pk_bf16_f32 v2, v2, v6
	global_store_dwordx2 v[4:5], v[2:3], off offset:96
	v_mul_f32_e32 v2, v28, v0
	v_mul_f32_e32 v6, v29, v0
	v_mul_f32_e32 v3, v30, v0
	v_mul_f32_e32 v0, v31, v0
	s_add_i32 s29, s29, s0
	v_cvt_pk_bf16_f32 v3, v3, v0
	v_cvt_pk_bf16_f32 v2, v2, v6
	s_cmpk_gt_i32 s29, 0xfff
	global_store_dwordx2 v[4:5], v[2:3], off offset:112
	s_cbranch_scc1 .LBB0_786

.LBB0_789:
	v_add_f32_e32 v0, v141, v0
	v_div_scale_f32 v36, s[40:41], v0, v0, 1.0
	v_rcp_f32_e32 v37, v36
	v_div_scale_f32 v38, vcc, 1.0, v0, 1.0
	v_fma_f32 v39, -v36, v37, 1.0
	v_fmac_f32_e32 v37, v39, v37
	v_mul_f32_e32 v39, v38, v37
	v_fma_f32 v40, -v36, v39, v38
	v_fmac_f32_e32 v39, v40, v37
	v_fma_f32 v36, -v36, v39, v38
	v_div_fmas_f32 v36, v36, v37, v39
	v_div_fixup_f32 v36, v36, v0, 1.0
	v_lshlrev_b32_e32 v0, 1, v134
	v_lshl_add_u64 v[34:35], v[34:35], 0, v[0:1]
	v_mul_f32_e32 v0, v18, v36
	v_mul_f32_e32 v18, v19, v36
	v_mul_f32_e32 v19, v20, v36
	v_mul_f32_e32 v20, v21, v36
	v_cvt_pk_bf16_f32 v19, v19, v20
	v_cvt_pk_bf16_f32 v18, v0, v18
	s_waitcnt vmcnt(0)
	global_store_dwordx2 v[34:35], v[18:19], off
	v_mul_f32_e32 v0, v22, v36
	v_mul_f32_e32 v18, v23, v36
	v_mul_f32_e32 v19, v24, v36
	v_mul_f32_e32 v20, v25, v36
	v_cvt_pk_bf16_f32 v19, v19, v20
	v_cvt_pk_bf16_f32 v18, v0, v18
	global_store_dwordx2 v[34:35], v[18:19], off offset:16
	v_mul_f32_e32 v0, v26, v36
	v_mul_f32_e32 v18, v27, v36
	v_mul_f32_e32 v19, v28, v36
	v_mul_f32_e32 v20, v29, v36
	v_cvt_pk_bf16_f32 v19, v19, v20
	v_cvt_pk_bf16_f32 v18, v0, v18
	global_store_dwordx2 v[34:35], v[18:19], off offset:32
	v_mul_f32_e32 v0, v30, v36
	v_mul_f32_e32 v18, v31, v36
	v_cvt_pk_bf16_f32 v18, v0, v18
	v_mul_f32_e32 v0, v2, v36
	v_mul_f32_e32 v2, v3, v36
	v_mul_f32_e32 v3, v4, v36
	v_mul_f32_e32 v4, v5, v36
	v_cvt_pk_bf16_f32 v3, v3, v4
	v_cvt_pk_bf16_f32 v2, v0, v2
	global_store_dwordx2 v[34:35], v[2:3], off offset:64
	v_mul_f32_e32 v0, v6, v36
	v_mul_f32_e32 v2, v7, v36
	v_mul_f32_e32 v3, v8, v36
	v_mul_f32_e32 v4, v9, v36
	v_cvt_pk_bf16_f32 v3, v3, v4
	v_cvt_pk_bf16_f32 v2, v0, v2
	global_store_dwordx2 v[34:35], v[2:3], off offset:80
	v_mul_f32_e32 v0, v10, v36
	v_mul_f32_e32 v2, v11, v36
	v_mul_f32_e32 v3, v12, v36
	v_mul_f32_e32 v4, v13, v36
	v_cvt_pk_bf16_f32 v3, v3, v4
	v_cvt_pk_bf16_f32 v2, v0, v2
	v_mul_f32_e32 v19, v32, v36
	v_mul_f32_e32 v20, v33, v36
	global_store_dwordx2 v[34:35], v[2:3], off offset:96
	v_mul_f32_e32 v0, v14, v36
	v_mul_f32_e32 v2, v15, v36
	v_mul_f32_e32 v3, v16, v36
	v_mul_f32_e32 v4, v17, v36
	v_cvt_pk_bf16_f32 v19, v19, v20
	v_cvt_pk_bf16_f32 v3, v3, v4
	v_cvt_pk_bf16_f32 v2, v0, v2
	global_store_dwordx2 v[34:35], v[18:19], off offset:48
	global_store_dwordx2 v[34:35], v[2:3], off offset:112

.LBB0_876:
	v_mov_b32_e32 v0, v177
	v_lshl_or_b32 v2, s16, 12, v178
	s_nop 0
	v_permlane32_swap_b32_e32 v177, v0
	v_add_f32_e32 v0, v177, v0
	v_div_scale_f32 v4, s[8:9], v0, v0, 1.0
	v_rcp_f32_e32 v5, v4
	v_ashrrev_i32_e32 v3, 31, v2
	v_lshlrev_b64 v[2:3], 11, v[2:3]
	v_lshl_add_u64 v[2:3], s[4:5], 0, v[2:3]
	v_fma_f32 v6, -v4, v5, 1.0
	v_fmac_f32_e32 v5, v6, v5
	v_div_scale_f32 v6, vcc, 1.0, v0, 1.0
	v_mul_f32_e32 v7, v6, v5
	v_fma_f32 v8, -v4, v7, v6
	v_fmac_f32_e32 v7, v8, v5
	v_fma_f32 v4, -v4, v7, v6
	v_div_fmas_f32 v4, v4, v5, v7
	s_mulk_i32 s10, 0x180
	v_div_fixup_f32 v0, v4, v0, 1.0
	v_lshl_add_u64 v[2:3], v[2:3], 0, s[10:11]
	v_mov_b32_e32 v177, v1
	v_mul_f32_e32 v4, v96, v0
	v_mul_f32_e32 v6, v97, v0
	v_mul_f32_e32 v5, v98, v0
	v_mul_f32_e32 v7, v99, v0
	v_lshl_add_u64 v[2:3], v[2:3], 0, v[176:177]
	v_cvt_pk_bf16_f32 v5, v5, v7
	v_cvt_pk_bf16_f32 v4, v4, v6
	s_waitcnt vmcnt(0)
	global_store_dwordx2 v[2:3], v[4:5], off
	v_mul_f32_e32 v4, v100, v0
	v_mul_f32_e32 v6, v101, v0
	v_mul_f32_e32 v5, v102, v0
	v_mul_f32_e32 v7, v103, v0
	v_cvt_pk_bf16_f32 v5, v5, v7
	v_cvt_pk_bf16_f32 v4, v4, v6
	global_store_dwordx2 v[2:3], v[4:5], off offset:16
	v_mul_f32_e32 v4, v104, v0
	v_mul_f32_e32 v6, v105, v0
	v_mul_f32_e32 v5, v106, v0
	v_mul_f32_e32 v7, v107, v0
	v_cvt_pk_bf16_f32 v5, v5, v7
	v_cvt_pk_bf16_f32 v4, v4, v6
	global_store_dwordx2 v[2:3], v[4:5], off offset:32
	v_mul_f32_e32 v4, v108, v0
	v_mul_f32_e32 v6, v109, v0
	v_mul_f32_e32 v5, v110, v0
	v_mul_f32_e32 v7, v111, v0
	v_cvt_pk_bf16_f32 v5, v5, v7
	v_cvt_pk_bf16_f32 v4, v4, v6
	global_store_dwordx2 v[2:3], v[4:5], off offset:48
	v_mul_f32_e32 v4, v80, v0
	v_mul_f32_e32 v6, v81, v0
	v_mul_f32_e32 v5, v82, v0
	v_mul_f32_e32 v7, v83, v0
	v_cvt_pk_bf16_f32 v5, v5, v7
	v_cvt_pk_bf16_f32 v4, v4, v6
	global_store_dwordx2 v[2:3], v[4:5], off offset:64
	v_mul_f32_e32 v4, v84, v0
	v_mul_f32_e32 v6, v85, v0
	v_mul_f32_e32 v5, v86, v0
	v_mul_f32_e32 v7, v87, v0
	v_cvt_pk_bf16_f32 v5, v5, v7
	v_cvt_pk_bf16_f32 v4, v4, v6
	global_store_dwordx2 v[2:3], v[4:5], off offset:80
	v_mul_f32_e32 v4, v88, v0
	v_mul_f32_e32 v6, v89, v0
	v_mul_f32_e32 v5, v90, v0
	v_mul_f32_e32 v7, v91, v0
	v_cvt_pk_bf16_f32 v5, v5, v7
	v_cvt_pk_bf16_f32 v4, v4, v6
	global_store_dwordx2 v[2:3], v[4:5], off offset:96
	v_mul_f32_e32 v4, v92, v0
	v_mul_f32_e32 v6, v93, v0
	v_mul_f32_e32 v5, v94, v0
	v_mul_f32_e32 v7, v95, v0
	v_cvt_pk_bf16_f32 v5, v5, v7
	v_cvt_pk_bf16_f32 v4, v4, v6
	global_store_dwordx2 v[2:3], v[4:5], off offset:112
	v_mul_f32_e32 v4, v64, v0
	v_mul_f32_e32 v6, v65, v0
	v_mul_f32_e32 v5, v66, v0
	v_mul_f32_e32 v7, v67, v0
	v_cvt_pk_bf16_f32 v5, v5, v7
	v_cvt_pk_bf16_f32 v4, v4, v6
	global_store_dwordx2 v[2:3], v[4:5], off offset:128
	v_mul_f32_e32 v4, v68, v0
	v_mul_f32_e32 v6, v69, v0
	v_mul_f32_e32 v5, v70, v0
	v_mul_f32_e32 v7, v71, v0
	v_cvt_pk_bf16_f32 v5, v5, v7
	v_cvt_pk_bf16_f32 v4, v4, v6
	global_store_dwordx2 v[2:3], v[4:5], off offset:144
	v_mul_f32_e32 v4, v72, v0
	v_mul_f32_e32 v6, v73, v0
	v_mul_f32_e32 v5, v74, v0
	v_mul_f32_e32 v7, v75, v0
	v_cvt_pk_bf16_f32 v5, v5, v7
	v_cvt_pk_bf16_f32 v4, v4, v6
	global_store_dwordx2 v[2:3], v[4:5], off offset:160
	v_mul_f32_e32 v4, v76, v0
	v_mul_f32_e32 v6, v77, v0
	v_mul_f32_e32 v5, v78, v0
	v_mul_f32_e32 v7, v79, v0
	v_cvt_pk_bf16_f32 v5, v5, v7
	v_cvt_pk_bf16_f32 v4, v4, v6
	global_store_dwordx2 v[2:3], v[4:5], off offset:176
	v_mul_f32_e32 v4, v48, v0
	v_mul_f32_e32 v6, v49, v0
	v_mul_f32_e32 v5, v50, v0
	v_mul_f32_e32 v7, v51, v0
	v_cvt_pk_bf16_f32 v5, v5, v7
	v_cvt_pk_bf16_f32 v4, v4, v6
	global_store_dwordx2 v[2:3], v[4:5], off offset:192
	v_mul_f32_e32 v4, v52, v0
	v_mul_f32_e32 v6, v53, v0
	v_mul_f32_e32 v5, v54, v0
	v_mul_f32_e32 v7, v55, v0
	v_cvt_pk_bf16_f32 v5, v5, v7
	v_cvt_pk_bf16_f32 v4, v4, v6
	global_store_dwordx2 v[2:3], v[4:5], off offset:208
	v_mul_f32_e32 v4, v56, v0
	v_mul_f32_e32 v6, v57, v0
	v_mul_f32_e32 v5, v58, v0
	v_mul_f32_e32 v7, v59, v0
	v_cvt_pk_bf16_f32 v5, v5, v7
	v_cvt_pk_bf16_f32 v4, v4, v6
	global_store_dwordx2 v[2:3], v[4:5], off offset:224
	v_mul_f32_e32 v4, v60, v0
	v_mul_f32_e32 v6, v61, v0
	v_mul_f32_e32 v5, v62, v0
	v_mul_f32_e32 v7, v63, v0
	v_cvt_pk_bf16_f32 v5, v5, v7
	v_cvt_pk_bf16_f32 v4, v4, v6
	global_store_dwordx2 v[2:3], v[4:5], off offset:240
	v_mul_f32_e32 v4, v32, v0
	v_mul_f32_e32 v6, v33, v0
	v_mul_f32_e32 v5, v34, v0
	v_mul_f32_e32 v7, v35, v0
	v_cvt_pk_bf16_f32 v5, v5, v7
	v_cvt_pk_bf16_f32 v4, v4, v6
	global_store_dwordx2 v[2:3], v[4:5], off offset:256
	v_mul_f32_e32 v4, v36, v0
	v_mul_f32_e32 v6, v37, v0
	v_mul_f32_e32 v5, v38, v0
	v_mul_f32_e32 v7, v39, v0
	v_cvt_pk_bf16_f32 v5, v5, v7
	v_cvt_pk_bf16_f32 v4, v4, v6
	global_store_dwordx2 v[2:3], v[4:5], off offset:272
	v_mul_f32_e32 v4, v40, v0
	v_mul_f32_e32 v6, v41, v0
	v_mul_f32_e32 v5, v42, v0
	v_mul_f32_e32 v7, v43, v0
	v_cvt_pk_bf16_f32 v5, v5, v7
	v_cvt_pk_bf16_f32 v4, v4, v6
	global_store_dwordx2 v[2:3], v[4:5], off offset:288
	v_mul_f32_e32 v4, v44, v0
	v_mul_f32_e32 v6, v45, v0
	v_mul_f32_e32 v5, v46, v0
	v_mul_f32_e32 v7, v47, v0
	v_cvt_pk_bf16_f32 v5, v5, v7
	v_cvt_pk_bf16_f32 v4, v4, v6
	global_store_dwordx2 v[2:3], v[4:5], off offset:304
	v_mul_f32_e32 v4, v16, v0
	v_mul_f32_e32 v6, v17, v0
	v_mul_f32_e32 v5, v18, v0
	v_mul_f32_e32 v7, v19, v0
	v_cvt_pk_bf16_f32 v5, v5, v7
	v_cvt_pk_bf16_f32 v4, v4, v6
	global_store_dwordx2 v[2:3], v[4:5], off offset:320
	v_mul_f32_e32 v4, v20, v0
	v_mul_f32_e32 v6, v21, v0
	v_mul_f32_e32 v5, v22, v0
	v_mul_f32_e32 v7, v23, v0
	v_cvt_pk_bf16_f32 v5, v5, v7
	v_cvt_pk_bf16_f32 v4, v4, v6
	global_store_dwordx2 v[2:3], v[4:5], off offset:336
	v_mul_f32_e32 v4, v24, v0
	v_mul_f32_e32 v6, v25, v0
	v_mul_f32_e32 v5, v26, v0
	v_mul_f32_e32 v7, v27, v0
	v_cvt_pk_bf16_f32 v5, v5, v7
	v_cvt_pk_bf16_f32 v4, v4, v6
	global_store_dwordx2 v[2:3], v[4:5], off offset:352
	v_mul_f32_e32 v4, v28, v0
	v_mul_f32_e32 v6, v29, v0
	v_mul_f32_e32 v5, v30, v0
	v_mul_f32_e32 v0, v31, v0
	s_add_i32 s14, s14, s0
	v_cvt_pk_bf16_f32 v5, v5, v0
	v_cvt_pk_bf16_f32 v4, v4, v6
	s_cmpk_gt_i32 s14, 0xfff
	global_store_dwordx2 v[2:3], v[4:5], off offset:368
	s_cbranch_scc1 .LBB0_884

.LBB0_1396:
	v_lshl_add_u64 v[22:23], v[8:9], 0, s[8:9]
	v_add_co_u32_e32 v24, vcc, 0x12390000, v22
	s_mov_b32 s5, 0x12391000
	s_nop 0
	v_addc_co_u32_e32 v25, vcc, 0, v23, vcc
	global_load_dwordx4 v[18:21], v[24:25], off
	v_add_co_u32_e32 v22, vcc, s5, v22
	s_add_u32 s8, s8, 0x2000
	s_nop 0
	v_addc_co_u32_e32 v23, vcc, 0, v23, vcc
	s_addc_u32 s9, s9, 0
	s_cmpk_lg_u32 s8, 0x8000
	s_waitcnt vmcnt(0)
	v_lshlrev_b32_e32 v26, 16, v18
	v_and_b32_e32 v27, 0xffff0000, v18
	v_lshlrev_b32_e32 v18, 16, v19
	v_and_b32_e32 v19, 0xffff0000, v19
	v_pk_add_f32 v[14:15], v[14:15], v[18:19]
	v_lshlrev_b32_e32 v18, 16, v20
	v_and_b32_e32 v19, 0xffff0000, v20
	v_pk_add_f32 v[18:19], v[12:13], v[18:19]
	v_lshlrev_b32_e32 v12, 16, v21
	v_and_b32_e32 v13, 0xffff0000, v21
	v_pk_add_f32 v[20:21], v[10:11], v[12:13]
	global_load_dwordx4 v[10:13], v[24:25], off offset:1024
	v_pk_add_f32 v[16:17], v[16:17], v[26:27]
	s_waitcnt vmcnt(0)
	v_lshlrev_b32_e32 v26, 16, v10
	v_and_b32_e32 v27, 0xffff0000, v10
	v_lshlrev_b32_e32 v10, 16, v11
	v_and_b32_e32 v11, 0xffff0000, v11
	v_pk_add_f32 v[14:15], v[14:15], v[10:11]
	v_lshlrev_b32_e32 v10, 16, v12
	v_and_b32_e32 v11, 0xffff0000, v12
	v_pk_add_f32 v[18:19], v[18:19], v[10:11]
	v_lshlrev_b32_e32 v10, 16, v13
	v_and_b32_e32 v11, 0xffff0000, v13
	v_pk_add_f32 v[20:21], v[20:21], v[10:11]
	global_load_dwordx4 v[10:13], v[24:25], off offset:2048
	v_pk_add_f32 v[16:17], v[16:17], v[26:27]
	s_waitcnt vmcnt(0)
	v_lshlrev_b32_e32 v26, 16, v10
	v_and_b32_e32 v27, 0xffff0000, v10
	v_lshlrev_b32_e32 v10, 16, v11
	v_and_b32_e32 v11, 0xffff0000, v11
	v_pk_add_f32 v[14:15], v[14:15], v[10:11]
	v_lshlrev_b32_e32 v10, 16, v12
	v_and_b32_e32 v11, 0xffff0000, v12
	v_pk_add_f32 v[18:19], v[18:19], v[10:11]
	v_lshlrev_b32_e32 v10, 16, v13
	v_and_b32_e32 v11, 0xffff0000, v13
	v_pk_add_f32 v[20:21], v[20:21], v[10:11]
	global_load_dwordx4 v[10:13], v[24:25], off offset:3072
	v_pk_add_f32 v[16:17], v[16:17], v[26:27]
	s_waitcnt vmcnt(0)
	v_lshlrev_b32_e32 v24, 16, v10
	v_and_b32_e32 v25, 0xffff0000, v10
	v_lshlrev_b32_e32 v10, 16, v11
	v_and_b32_e32 v11, 0xffff0000, v11
	v_pk_add_f32 v[14:15], v[14:15], v[10:11]
	v_lshlrev_b32_e32 v10, 16, v12
	v_and_b32_e32 v11, 0xffff0000, v12
	v_pk_add_f32 v[18:19], v[18:19], v[10:11]
	v_lshlrev_b32_e32 v10, 16, v13
	v_and_b32_e32 v11, 0xffff0000, v13
	v_pk_add_f32 v[20:21], v[20:21], v[10:11]
	global_load_dwordx4 v[10:13], v[22:23], off
	v_pk_add_f32 v[16:17], v[16:17], v[24:25]
	s_waitcnt vmcnt(0)
	v_lshlrev_b32_e32 v24, 16, v10
	v_and_b32_e32 v25, 0xffff0000, v10
	v_lshlrev_b32_e32 v10, 16, v11
	v_and_b32_e32 v11, 0xffff0000, v11
	v_pk_add_f32 v[14:15], v[14:15], v[10:11]
	v_lshlrev_b32_e32 v10, 16, v12
	v_and_b32_e32 v11, 0xffff0000, v12
	v_pk_add_f32 v[18:19], v[18:19], v[10:11]
	v_lshlrev_b32_e32 v10, 16, v13
	v_and_b32_e32 v11, 0xffff0000, v13
	v_pk_add_f32 v[20:21], v[20:21], v[10:11]
	global_load_dwordx4 v[10:13], v[22:23], off offset:1024
	v_pk_add_f32 v[16:17], v[16:17], v[24:25]
	s_waitcnt vmcnt(0)
	v_lshlrev_b32_e32 v24, 16, v10
	v_and_b32_e32 v25, 0xffff0000, v10
	v_lshlrev_b32_e32 v10, 16, v11
	v_and_b32_e32 v11, 0xffff0000, v11
	v_pk_add_f32 v[14:15], v[14:15], v[10:11]
	v_lshlrev_b32_e32 v10, 16, v12
	v_and_b32_e32 v11, 0xffff0000, v12
	v_pk_add_f32 v[18:19], v[18:19], v[10:11]
	v_lshlrev_b32_e32 v10, 16, v13
	v_and_b32_e32 v11, 0xffff0000, v13
	v_pk_add_f32 v[20:21], v[20:21], v[10:11]
	global_load_dwordx4 v[10:13], v[22:23], off offset:2048
	v_pk_add_f32 v[16:17], v[16:17], v[24:25]
	s_waitcnt vmcnt(0)
	v_lshlrev_b32_e32 v24, 16, v10
	v_and_b32_e32 v25, 0xffff0000, v10
	v_lshlrev_b32_e32 v10, 16, v11
	v_and_b32_e32 v11, 0xffff0000, v11
	v_pk_add_f32 v[10:11], v[14:15], v[10:11]
	v_lshlrev_b32_e32 v14, 16, v12
	v_and_b32_e32 v15, 0xffff0000, v12
	v_lshlrev_b32_e32 v12, 16, v13
	v_and_b32_e32 v13, 0xffff0000, v13
	v_pk_add_f32 v[16:17], v[16:17], v[24:25]
	v_pk_add_f32 v[24:25], v[18:19], v[14:15]
	v_pk_add_f32 v[26:27], v[20:21], v[12:13]
	global_load_dwordx4 v[18:21], v[22:23], off offset:3072
	s_waitcnt vmcnt(0)
	v_lshlrev_b32_e32 v12, 16, v18
	v_and_b32_e32 v13, 0xffff0000, v18
	v_pk_add_f32 v[16:17], v[16:17], v[12:13]
	v_lshlrev_b32_e32 v12, 16, v19
	v_and_b32_e32 v13, 0xffff0000, v19
	v_pk_add_f32 v[14:15], v[10:11], v[12:13]
	v_lshlrev_b32_e32 v10, 16, v20
	v_and_b32_e32 v11, 0xffff0000, v20
	v_pk_add_f32 v[12:13], v[24:25], v[10:11]
	v_lshlrev_b32_e32 v10, 16, v21
	v_and_b32_e32 v11, 0xffff0000, v21
	v_pk_add_f32 v[10:11], v[26:27], v[10:11]
	s_cbranch_scc1 .LBB0_1396
	ds_swizzle_b32 v0, v16 offset:swizzle(SWAP,8)
	ds_swizzle_b32 v8, v17 offset:swizzle(SWAP,8)
	ds_swizzle_b32 v9, v14 offset:swizzle(SWAP,8)
	ds_swizzle_b32 v19, v15 offset:swizzle(SWAP,8)
	ds_swizzle_b32 v20, v12 offset:swizzle(SWAP,8)
	s_waitcnt lgkmcnt(0)
	v_add_f32_e32 v0, v16, v0
	s_waitcnt lgkmcnt(3)
	v_add_f32_e32 v16, v17, v8
	ds_swizzle_b32 v8, v0 offset:swizzle(SWAP,16)
	s_waitcnt lgkmcnt(3)
	v_add_f32_e32 v14, v14, v9
	ds_swizzle_b32 v21, v13 offset:swizzle(SWAP,8)
	ds_swizzle_b32 v22, v10 offset:swizzle(SWAP,8)
	ds_swizzle_b32 v17, v16 offset:swizzle(SWAP,16)
	s_waitcnt lgkmcnt(3)
	v_add_f32_e32 v8, v0, v8
	ds_swizzle_b32 v0, v14 offset:swizzle(SWAP,16)
	s_waitcnt lgkmcnt(1)
	v_add_f32_e32 v9, v16, v17
	v_mov_b32_e32 v16, v8
	s_waitcnt lgkmcnt(0)
	v_add_f32_e32 v14, v14, v0
	v_add_f32_e32 v0, v15, v19
	ds_swizzle_b32 v15, v0 offset:swizzle(SWAP,16)
	v_mov_b32_e32 v17, v9
	v_mov_b32_e32 v18, v14
	s_waitcnt lgkmcnt(0)
	v_add_f32_e32 v15, v0, v15
	v_add_f32_e32 v0, v12, v20
	ds_swizzle_b32 v12, v0 offset:swizzle(SWAP,16)
	v_mov_b32_e32 v19, v15
	v_permlane32_swap_b32_e32 v8, v16
	s_waitcnt lgkmcnt(0)
	v_add_f32_e32 v12, v0, v12
	v_add_f32_e32 v0, v13, v21
	ds_swizzle_b32 v13, v0 offset:swizzle(SWAP,16)
	v_mov_b32_e32 v20, v12
	v_permlane32_swap_b32_e32 v9, v17
	s_waitcnt lgkmcnt(0)
	v_add_f32_e32 v13, v0, v13
	v_add_f32_e32 v0, v10, v22
	ds_swizzle_b32 v10, v0 offset:swizzle(SWAP,16)
	ds_swizzle_b32 v22, v11 offset:swizzle(SWAP,8)
	v_mov_b32_e32 v21, v13
	v_permlane32_swap_b32_e32 v14, v18
	s_waitcnt lgkmcnt(1)
	v_add_f32_e32 v10, v0, v10
	s_waitcnt lgkmcnt(0)
	v_add_f32_e32 v0, v11, v22
	ds_swizzle_b32 v11, v0 offset:swizzle(SWAP,16)
	v_mov_b32_e32 v22, v10
	v_permlane32_swap_b32_e32 v15, v19
	s_waitcnt lgkmcnt(0)
	v_add_f32_e32 v11, v0, v11
	v_mov_b32_e32 v23, v11
	v_permlane32_swap_b32_e32 v12, v20
	v_permlane32_swap_b32_e32 v13, v21
	v_permlane32_swap_b32_e32 v10, v22
	v_permlane32_swap_b32_e32 v11, v23
	s_and_saveexec_b64 s[8:9], s[40:41]
	s_cbranch_execz .LBB0_1394
	s_ashr_i32 s5, s4, 31
	s_lshl_b64 s[14:15], s[4:5], 8
	v_lshl_add_u64 v[24:25], v[2:3], 0, s[14:15]
	v_pk_add_f32 v[8:9], v[8:9], v[16:17]
	s_mov_b32 s14, 0x3b800000
	v_pk_mul_f32 v[16:17], v[8:9], s[14:15] op_sel_hi:[1,0]
	v_pk_add_f32 v[8:9], v[14:15], v[18:19]
	v_pk_add_f32 v[10:11], v[10:11], v[22:23]
	v_pk_mul_f32 v[18:19], v[8:9], s[14:15] op_sel_hi:[1,0]
	v_pk_add_f32 v[8:9], v[12:13], v[20:21]
	v_pk_mul_f32 v[10:11], v[10:11], s[14:15] op_sel_hi:[1,0]
	v_pk_mul_f32 v[8:9], v[8:9], s[14:15] op_sel_hi:[1,0]
	s_lshl_b64 s[14:15], s[4:5], 7
	global_store_dwordx4 v[24:25], v[8:11], off offset:16
	v_lshl_add_u64 v[12:13], v[6:7], 0, s[14:15]
	global_store_dwordx4 v[24:25], v[16:19], off
	v_cvt_pk_bf16_f32 v11, v10, v11
	v_cvt_pk_bf16_f32 v10, v8, v9
	v_cvt_pk_bf16_f32 v9, v18, v19
	v_cvt_pk_bf16_f32 v8, v16, v17
	global_store_dwordx4 v[12:13], v[8:11], off
	s_branch .LBB0_1394

.LBB0_1404:
	s_or_b64 exec, exec, s[44:45]
	v_add_co_u32_e32 v8, vcc, 0x1bb90000, v8
	s_add_i32 s4, s4, s14
	v_cvt_pk_bf16_f32 v3, v10, s0
	v_addc_co_u32_e32 v9, vcc, 0, v9, vcc
	v_add_u32_e32 v2, s10, v2
	v_lshl_add_u64 v[4:5], v[4:5], 0, s[16:17]
	s_cmpk_gt_i32 s4, 0x7fff
	v_lshl_add_u64 v[6:7], v[6:7], 0, s[46:47]
	global_store_short v[8:9], v3, off offset:384
	s_cbranch_scc1 .LBB0_1428
.LBB0_1405:
	v_lshl_add_u64 v[8:9], s[58:59], 0, v[6:7]
	v_add_co_u32_e32 v8, vcc, 0x1b390000, v8
	v_subrev_u32_e32 v10, 24, v2
	s_nop 0
	v_addc_co_u32_e32 v9, vcc, 0, v9, vcc
	global_load_dword v25, v[8:9], off
	v_ashrrev_i32_e32 v11, 31, v10
	v_lshlrev_b64 v[10:11], 2, v[10:11]
	v_lshl_add_u64 v[12:13], s[0:1], 0, v[10:11]
	v_lshl_add_u64 v[10:11], s[8:9], 0, v[10:11]
	global_load_dword v23, v[12:13], off
	global_load_dword v24, v[10:11], off
	global_load_dword v20, v[8:9], off offset:256
	v_add_u32_e32 v10, -16, v2
	v_ashrrev_i32_e32 v11, 31, v10
	v_lshlrev_b64 v[10:11], 2, v[10:11]
	v_lshl_add_u64 v[12:13], s[0:1], 0, v[10:11]
	v_lshl_add_u64 v[10:11], s[8:9], 0, v[10:11]
	global_load_dword v21, v[12:13], off
	global_load_dword v22, v[10:11], off
	global_load_dword v19, v[8:9], off offset:512
	v_add_u32_e32 v10, -8, v2
	v_ashrrev_i32_e32 v11, 31, v10
	v_lshlrev_b64 v[10:11], 2, v[10:11]
	v_lshl_add_u64 v[12:13], s[0:1], 0, v[10:11]
	v_lshl_add_u64 v[10:11], s[8:9], 0, v[10:11]
	v_ashrrev_i32_e32 v3, 31, v2
	global_load_dword v16, v[12:13], off
	global_load_dword v17, v[10:11], off
	global_load_dword v15, v[8:9], off offset:768
	v_lshlrev_b64 v[8:9], 2, v[2:3]
	v_lshl_add_u64 v[10:11], s[0:1], 0, v[8:9]
	v_lshl_add_u64 v[8:9], s[8:9], 0, v[8:9]
	global_load_dword v3, v[10:11], off
	global_load_dword v18, v[8:9], off
	s_mov_b32 s5, 0x800000
	s_waitcnt vmcnt(0) lgkmcnt(0)
	ds_swizzle_b32 v8, v25 offset:swizzle(SWAP,1)
	s_waitcnt lgkmcnt(0)
	v_add_f32_e32 v8, v25, v8
	ds_swizzle_b32 v9, v8 offset:swizzle(SWAP,2)
	s_waitcnt lgkmcnt(0)
	v_add_f32_e32 v8, v8, v9
	ds_swizzle_b32 v9, v8 offset:swizzle(SWAP,4)
	s_waitcnt lgkmcnt(0)
	v_add_f32_e32 v8, v8, v9
	ds_swizzle_b32 v9, v8 offset:swizzle(SWAP,8)
	s_waitcnt lgkmcnt(0)
	v_add_f32_e32 v8, v8, v9
	ds_swizzle_b32 v9, v8 offset:swizzle(SWAP,16)
	s_waitcnt lgkmcnt(0)
	v_add_f32_e32 v8, v8, v9
	v_mov_b32_e32 v9, v8
	s_nop 1
	v_permlane32_swap_b32_e32 v8, v9
	v_add_f32_e32 v8, v8, v9
	ds_swizzle_b32 v9, v20 offset:swizzle(SWAP,1)
	v_fmac_f32_e32 v25, 0xbc800000, v8
	v_mul_f32_e32 v8, v25, v25
	ds_swizzle_b32 v8, v8 offset:swizzle(SWAP,1)
	s_waitcnt lgkmcnt(1)
	v_add_f32_e32 v9, v20, v9
	ds_swizzle_b32 v10, v9 offset:swizzle(SWAP,2)
	s_waitcnt lgkmcnt(1)
	v_fmac_f32_e32 v8, v25, v25
	s_waitcnt lgkmcnt(0)
	v_add_f32_e32 v9, v9, v10
	ds_swizzle_b32 v10, v9 offset:swizzle(SWAP,4)
	s_waitcnt lgkmcnt(0)
	v_add_f32_e32 v9, v9, v10
	ds_swizzle_b32 v10, v9 offset:swizzle(SWAP,8)
	s_waitcnt lgkmcnt(0)
	v_add_f32_e32 v9, v9, v10
	ds_swizzle_b32 v10, v9 offset:swizzle(SWAP,16)
	s_waitcnt lgkmcnt(0)
	v_add_f32_e32 v9, v9, v10
	v_mov_b32_e32 v10, v9
	s_nop 1
	v_permlane32_swap_b32_e32 v9, v10
	v_add_f32_e32 v10, v9, v10
	ds_swizzle_b32 v9, v19 offset:swizzle(SWAP,1)
	v_fmac_f32_e32 v20, 0xbc800000, v10
	s_waitcnt lgkmcnt(0)
	v_add_f32_e32 v9, v19, v9
	ds_swizzle_b32 v11, v9 offset:swizzle(SWAP,2)
	s_waitcnt lgkmcnt(0)
	v_add_f32_e32 v9, v9, v11
	ds_swizzle_b32 v11, v9 offset:swizzle(SWAP,4)
	s_waitcnt lgkmcnt(0)
	v_add_f32_e32 v9, v9, v11
	ds_swizzle_b32 v11, v9 offset:swizzle(SWAP,8)
	s_waitcnt lgkmcnt(0)
	v_add_f32_e32 v9, v9, v11
	ds_swizzle_b32 v11, v9 offset:swizzle(SWAP,16)
	s_waitcnt lgkmcnt(0)
	v_add_f32_e32 v9, v9, v11
	v_mov_b32_e32 v11, v9
	s_nop 1
	v_permlane32_swap_b32_e32 v9, v11
	v_add_f32_e32 v12, v9, v11
	ds_swizzle_b32 v9, v15 offset:swizzle(SWAP,1)
	v_fmac_f32_e32 v19, 0xbc800000, v12
	s_waitcnt lgkmcnt(0)
	v_add_f32_e32 v9, v15, v9
	ds_swizzle_b32 v11, v9 offset:swizzle(SWAP,2)
	s_waitcnt lgkmcnt(0)
	v_add_f32_e32 v9, v9, v11
	ds_swizzle_b32 v11, v9 offset:swizzle(SWAP,4)
	s_waitcnt lgkmcnt(0)
	v_add_f32_e32 v9, v9, v11
	ds_swizzle_b32 v11, v9 offset:swizzle(SWAP,8)
	s_waitcnt lgkmcnt(0)
	v_add_f32_e32 v9, v9, v11
	ds_swizzle_b32 v11, v9 offset:swizzle(SWAP,16)
	s_waitcnt lgkmcnt(0)
	v_add_f32_e32 v9, v9, v11
	v_mov_b32_e32 v11, v9
	s_nop 1
	v_permlane32_swap_b32_e32 v9, v11
	v_add_f32_e32 v26, v9, v11
	ds_swizzle_b32 v9, v8 offset:swizzle(SWAP,2)
	v_fmac_f32_e32 v15, 0xbc800000, v26
	s_waitcnt lgkmcnt(0)
	v_add_f32_e32 v8, v8, v9
	ds_swizzle_b32 v9, v8 offset:swizzle(SWAP,4)
	s_waitcnt lgkmcnt(0)
	v_add_f32_e32 v8, v8, v9
	ds_swizzle_b32 v9, v8 offset:swizzle(SWAP,8)
	s_waitcnt lgkmcnt(0)
	v_add_f32_e32 v8, v8, v9
	ds_swizzle_b32 v9, v8 offset:swizzle(SWAP,16)
	s_waitcnt lgkmcnt(0)
	v_add_f32_e32 v9, v8, v9
	v_mul_f32_e32 v8, v20, v20
	ds_swizzle_b32 v8, v8 offset:swizzle(SWAP,1)
	v_mov_b32_e32 v11, v9
	s_waitcnt lgkmcnt(0)
	v_fmac_f32_e32 v8, v20, v20
	ds_swizzle_b32 v10, v8 offset:swizzle(SWAP,2)
	v_permlane32_swap_b32_e32 v9, v11
	s_waitcnt lgkmcnt(0)
	v_add_f32_e32 v8, v8, v10
	ds_swizzle_b32 v10, v8 offset:swizzle(SWAP,4)
	s_waitcnt lgkmcnt(0)
	v_add_f32_e32 v8, v8, v10
	ds_swizzle_b32 v10, v8 offset:swizzle(SWAP,8)
	s_waitcnt lgkmcnt(0)
	v_add_f32_e32 v8, v8, v10
	ds_swizzle_b32 v10, v8 offset:swizzle(SWAP,16)
	s_waitcnt lgkmcnt(0)
	v_add_f32_e32 v8, v8, v10
	v_mov_b32_e32 v10, v8
	s_nop 1
	v_permlane32_swap_b32_e32 v8, v10
	v_pk_add_f32 v[8:9], v[8:9], v[10:11]
	v_mov_b32_e32 v10, 0x3727c5ac
	v_pk_fma_f32 v[8:9], v[8:9], s[18:19], v[10:11] op_sel_hi:[1,0,0]
	s_nop 0
	v_mul_f32_e32 v10, 0x4b800000, v9
	v_cmp_gt_f32_e64 s[44:45], s5, v9
	v_cmp_gt_f32_e32 vcc, s5, v8
	s_nop 0
	v_cndmask_b32_e64 v9, v9, v10, s[44:45]
	v_rsq_f32_e32 v9, v9
	s_nop 0
	v_mul_f32_e32 v10, 0x45800000, v9
	v_cndmask_b32_e64 v9, v9, v10, s[44:45]
	v_mul_f32_e32 v10, v19, v19
	ds_swizzle_b32 v10, v10 offset:swizzle(SWAP,1)
	v_mul_f32_e32 v9, v25, v9
	v_fma_f32 v9, v0, v9, v14
	ds_swizzle_b32 v25, v9 offset:swizzle(SWAP,8)
	s_waitcnt lgkmcnt(1)
	v_fmac_f32_e32 v10, v19, v19
	ds_swizzle_b32 v11, v10 offset:swizzle(SWAP,2)
	s_waitcnt lgkmcnt(0)
	v_add_f32_e32 v10, v10, v11
	ds_swizzle_b32 v11, v10 offset:swizzle(SWAP,4)
	s_waitcnt lgkmcnt(0)
	v_add_f32_e32 v10, v10, v11
	ds_swizzle_b32 v11, v10 offset:swizzle(SWAP,8)
	s_waitcnt lgkmcnt(0)
	v_add_f32_e32 v10, v10, v11
	ds_swizzle_b32 v11, v10 offset:swizzle(SWAP,16)
	s_waitcnt lgkmcnt(0)
	v_add_f32_e32 v11, v10, v11
	v_mul_f32_e32 v10, v15, v15
	ds_swizzle_b32 v10, v10 offset:swizzle(SWAP,1)
	v_mov_b32_e32 v13, v11
	s_waitcnt lgkmcnt(0)
	v_fmac_f32_e32 v10, v15, v15
	ds_swizzle_b32 v12, v10 offset:swizzle(SWAP,2)
	v_permlane32_swap_b32_e32 v11, v13
	s_waitcnt lgkmcnt(0)
	v_add_f32_e32 v10, v10, v12
	ds_swizzle_b32 v12, v10 offset:swizzle(SWAP,4)
	s_waitcnt lgkmcnt(0)
	v_add_f32_e32 v10, v10, v12
	ds_swizzle_b32 v12, v10 offset:swizzle(SWAP,8)
	s_waitcnt lgkmcnt(0)
	v_add_f32_e32 v10, v10, v12
	ds_swizzle_b32 v12, v10 offset:swizzle(SWAP,16)
	s_waitcnt lgkmcnt(0)
	v_add_f32_e32 v10, v10, v12
	v_mov_b32_e32 v12, v10
	s_nop 1
	v_permlane32_swap_b32_e32 v10, v12
	s_and_saveexec_b64 s[44:45], s[40:41]
	s_cbranch_execz .LBB0_1411
	v_mul_f32_e32 v23, v23, v9
	v_mul_f32_e32 v24, v24, v25
	s_and_saveexec_b64 s[48:49], s[42:43]
	s_xor_b64 s[48:49], exec, s[48:49]
	v_add_f32_e32 v9, v23, v24
	s_andn2_saveexec_b64 s[48:49], s[48:49]
	v_sub_f32_e32 v9, v23, v24
	s_or_b64 exec, exec, s[48:49]
.LBB0_1411:
	s_or_b64 exec, exec, s[44:45]
	v_mul_f32_e32 v23, 0x4b800000, v8
	v_cndmask_b32_e32 v8, v8, v23, vcc
	v_rsq_f32_e32 v23, v8
	v_cvt_pk_bf16_f32 v26, v9, s0
	v_lshl_add_u64 v[8:9], s[58:59], 0, v[4:5]
	v_mul_f32_e32 v24, 0x45800000, v23
	v_cndmask_b32_e32 v23, v23, v24, vcc
	v_mul_f32_e32 v20, v20, v23
	v_fma_f32 v20, v0, v20, v14
	ds_swizzle_b32 v23, v20 offset:swizzle(SWAP,8)
	v_add_co_u32_e32 v24, vcc, 0x1bb90000, v8
	s_nop 1
	v_addc_co_u32_e32 v25, vcc, 0, v9, vcc
	global_store_short v[24:25], v26, off
	s_and_saveexec_b64 s[44:45], s[40:41]
	s_cbranch_execz .LBB0_1417
	v_mul_f32_e32 v21, v21, v20
	s_waitcnt lgkmcnt(0)
	v_mul_f32_e32 v22, v22, v23
	s_and_saveexec_b64 s[48:49], s[42:43]
	s_xor_b64 s[48:49], exec, s[48:49]
	v_add_f32_e32 v20, v21, v22
	s_andn2_saveexec_b64 s[48:49], s[48:49]
	v_sub_f32_e32 v20, v21, v22
	s_or_b64 exec, exec, s[48:49]
.LBB0_1417:
	s_or_b64 exec, exec, s[44:45]
	v_pk_add_f32 v[10:11], v[10:11], v[12:13]
	v_mov_b32_e32 v12, 0x3727c5ac
	v_pk_fma_f32 v[10:11], v[10:11], s[18:19], v[12:13] op_sel_hi:[1,0,0]
	s_nop 0
	v_mul_f32_e32 v12, 0x4b800000, v11
	v_cmp_gt_f32_e32 vcc, s5, v11
	v_cmp_gt_f32_e64 s[44:45], s5, v10
	s_nop 0
	v_cndmask_b32_e32 v11, v11, v12, vcc
	v_rsq_f32_e32 v11, v11
	v_cvt_pk_bf16_f32 v12, v20, s0
	v_mul_f32_e32 v13, 0x45800000, v11
	v_cndmask_b32_e32 v11, v11, v13, vcc
	v_mul_f32_e32 v11, v19, v11
	v_fma_f32 v11, v0, v11, v14
	ds_swizzle_b32 v13, v11 offset:swizzle(SWAP,8)
	v_add_co_u32_e32 v20, vcc, 0x1bb90000, v8
	s_nop 1
	v_addc_co_u32_e32 v21, vcc, 0, v9, vcc
	global_store_short v[20:21], v12, off offset:128
	s_and_saveexec_b64 s[48:49], s[40:41]
	s_cbranch_execz .LBB0_1423
	v_mul_f32_e32 v12, v16, v11
	s_waitcnt lgkmcnt(0)
	v_mul_f32_e32 v13, v17, v13
	s_and_saveexec_b64 s[52:53], s[42:43]
	s_xor_b64 s[52:53], exec, s[52:53]
	v_add_f32_e32 v11, v12, v13
	s_andn2_saveexec_b64 s[52:53], s[52:53]
	v_sub_f32_e32 v11, v12, v13
	s_or_b64 exec, exec, s[52:53]
.LBB0_1423:
	s_or_b64 exec, exec, s[48:49]
	v_mul_f32_e32 v12, 0x4b800000, v10
	v_cndmask_b32_e64 v10, v10, v12, s[44:45]
	v_rsq_f32_e32 v10, v10
	v_cvt_pk_bf16_f32 v16, v11, s0
	v_add_co_u32_e32 v12, vcc, 0x1bb90000, v8
	v_mul_f32_e32 v11, 0x45800000, v10
	v_cndmask_b32_e64 v10, v10, v11, s[44:45]
	v_mul_f32_e32 v10, v15, v10
	v_fma_f32 v10, v0, v10, v14
	ds_swizzle_b32 v11, v10 offset:swizzle(SWAP,8)
	s_waitcnt lgkmcnt(0)
	v_addc_co_u32_e32 v13, vcc, 0, v9, vcc
	global_store_short v[12:13], v16, off offset:256
	s_and_saveexec_b64 s[44:45], s[40:41]
	s_cbranch_execz .LBB0_1404
	v_mul_f32_e32 v3, v3, v10
	v_mul_f32_e32 v11, v18, v11
	s_and_saveexec_b64 s[48:49], s[42:43]
	s_xor_b64 s[48:49], exec, s[48:49]
	v_add_f32_e32 v10, v3, v11
	s_andn2_saveexec_b64 s[48:49], s[48:49]
	s_cbranch_execz .LBB0_1403
	v_sub_f32_e32 v10, v3, v11
	s_branch .LBB0_1403
